# v008 plus: GEMM K loops run the back-edge increments behind the last load segment's LDS reads and the pointer selects behind the first segment's LDS reads
# speedup vs baseline: 1.0220x; 1.0012x over previous
.LBB0_183:
	s_add_i32 s53, 0, 0x10000
	v_add_u32_e32 v142, s53, v147
	s_add_i32 s67, 0, 0x14000
	ds_read_b128 v[150:153], v142
	ds_read_b128 v[154:157], v142 offset:1024
	ds_read_b128 v[158:161], v142 offset:2048
	ds_read_b128 v[162:165], v142 offset:3072
	v_add_u32_e32 v142, s67, v147
	ds_read_b128 v[166:169], v142
	ds_read_b128 v[170:173], v142 offset:1024
	ds_read_b128 v[174:177], v142 offset:2048
	ds_read_b128 v[178:181], v142 offset:3072
	v_lshl_add_u64 v[144:145], s[4:5], 0, v[140:141]
	s_add_i32 m0, s59, 0xc000
	ds_read_b128 v[182:185], v149
	ds_read_b128 v[186:189], v149 offset:1024
	ds_read_b128 v[190:193], v149 offset:2048
	ds_read_b128 v[202:205], v149 offset:3072
	ds_read_b128 v[206:209], v149 offset:4096
	ds_read_b128 v[210:213], v149 offset:5120
	ds_read_b128 v[214:217], v149 offset:6144
	ds_read_b128 v[218:221], v149 offset:7168
	s_add_u32 s14, s4, 0xfffc0080
	s_addc_u32 s15, s5, -1
	s_cmp_eq_u32 s49, 12
	s_cselect_b32 s55, s21, s15
	s_cselect_b32 s54, s28, s14
	s_cselect_b32 s15, s29, s47
	s_cselect_b32 s14, s33, s37
	global_load_lds_dwordx4 v[144:145], off
	v_lshl_add_u64 v[144:145], s[4:5], 0, v[138:139]
	s_add_i32 m0, s59, 0xe000
	s_nop 0
	global_load_lds_dwordx4 v[144:145], off
	s_waitcnt vmcnt(8)
	s_waitcnt lgkmcnt(0)
	s_setprio 1
	s_barrier
	v_mfma_f32_16x16x32_bf16 v[126:129], v[150:153], v[182:185], v[126:129]
	v_mfma_f32_16x16x32_bf16 v[122:125], v[158:161], v[182:185], v[122:125]
	v_mfma_f32_16x16x32_bf16 v[110:113], v[150:153], v[190:193], v[110:113]
	v_mfma_f32_16x16x32_bf16 v[106:109], v[158:161], v[190:193], v[106:109]
	v_mfma_f32_16x16x32_bf16 v[94:97], v[150:153], v[206:209], v[94:97]
	v_mfma_f32_16x16x32_bf16 v[90:93], v[158:161], v[206:209], v[90:93]
	v_mfma_f32_16x16x32_bf16 v[78:81], v[150:153], v[214:217], v[78:81]
	v_mfma_f32_16x16x32_bf16 v[74:77], v[158:161], v[214:217], v[74:77]
	v_mfma_f32_16x16x32_bf16 v[126:129], v[154:157], v[186:189], v[126:129]
	v_mfma_f32_16x16x32_bf16 v[122:125], v[162:165], v[186:189], v[122:125]
	v_mfma_f32_16x16x32_bf16 v[110:113], v[154:157], v[202:205], v[110:113]
	v_mfma_f32_16x16x32_bf16 v[106:109], v[162:165], v[202:205], v[106:109]
	v_mfma_f32_16x16x32_bf16 v[94:97], v[154:157], v[210:213], v[94:97]
	v_mfma_f32_16x16x32_bf16 v[90:93], v[162:165], v[210:213], v[90:93]
	v_mfma_f32_16x16x32_bf16 v[78:81], v[154:157], v[218:221], v[78:81]
	v_mfma_f32_16x16x32_bf16 v[74:77], v[162:165], v[218:221], v[74:77]
	v_mfma_f32_16x16x32_bf16 v[118:121], v[166:169], v[182:185], v[118:121]
	v_mfma_f32_16x16x32_bf16 v[114:117], v[174:177], v[182:185], v[114:117]
	v_mfma_f32_16x16x32_bf16 v[102:105], v[166:169], v[190:193], v[102:105]
	v_mfma_f32_16x16x32_bf16 v[98:101], v[174:177], v[190:193], v[98:101]
	v_mfma_f32_16x16x32_bf16 v[86:89], v[166:169], v[206:209], v[86:89]
	v_mfma_f32_16x16x32_bf16 v[82:85], v[174:177], v[206:209], v[82:85]
	v_mfma_f32_16x16x32_bf16 v[70:73], v[166:169], v[214:217], v[70:73]
	v_mfma_f32_16x16x32_bf16 v[66:69], v[174:177], v[214:217], v[66:69]
	v_mfma_f32_16x16x32_bf16 v[118:121], v[170:173], v[186:189], v[118:121]
	v_mfma_f32_16x16x32_bf16 v[114:117], v[178:181], v[186:189], v[114:117]
	v_mfma_f32_16x16x32_bf16 v[102:105], v[170:173], v[202:205], v[102:105]
	v_mfma_f32_16x16x32_bf16 v[98:101], v[178:181], v[202:205], v[98:101]
	v_mfma_f32_16x16x32_bf16 v[86:89], v[170:173], v[210:213], v[86:89]
	v_mfma_f32_16x16x32_bf16 v[82:85], v[178:181], v[210:213], v[82:85]
	v_mfma_f32_16x16x32_bf16 v[70:73], v[170:173], v[218:221], v[70:73]
	v_mfma_f32_16x16x32_bf16 v[66:69], v[178:181], v[218:221], v[66:69]
	s_barrier
	s_setprio 0
	s_add_i32 s53, s53, s58
	v_lshl_add_u64 v[144:145], s[14:15], 0, v[134:135]
	s_mov_b32 m0, s53
	ds_read_b128 v[182:185], v149 offset:16384
	ds_read_b128 v[186:189], v149 offset:17408
	ds_read_b128 v[190:193], v149 offset:18432
	ds_read_b128 v[202:205], v149 offset:19456
	ds_read_b128 v[206:209], v149 offset:20480
	ds_read_b128 v[210:213], v149 offset:21504
	ds_read_b128 v[214:217], v149 offset:22528
	ds_read_b128 v[218:221], v149 offset:23552
	global_load_lds_dwordx4 v[144:145], off
	s_add_i32 m0, s53, 0x2000
	s_add_u32 s68, s14, 0x40000
	v_lshl_add_u64 v[222:223], s[14:15], 0, v[130:131]
	s_addc_u32 s69, s15, 0
	s_add_i32 s53, s67, s58
	global_load_lds_dwordx4 v[222:223], off
	v_lshl_add_u64 v[232:233], s[68:69], 0, v[134:135]
	s_mov_b32 m0, s53
	v_lshl_add_u64 v[234:235], s[54:55], 0, v[132:133]
	global_load_lds_dwordx4 v[232:233], off
	v_lshl_add_u64 v[232:233], s[68:69], 0, v[130:131]
	s_add_i32 m0, s53, 0x2000
	s_nop 0
	global_load_lds_dwordx4 v[232:233], off
	v_lshl_add_u64 v[232:233], s[54:55], 0, v[136:137]
	s_mov_b32 m0, s59
	s_nop 0
	global_load_lds_dwordx4 v[232:233], off
	s_mov_b32 m0, s60
	s_nop 0
	global_load_lds_dwordx4 v[234:235], off
	s_waitcnt vmcnt(8)
	s_waitcnt lgkmcnt(0)
	s_setprio 1
	s_barrier
	v_mfma_f32_16x16x32_bf16 v[62:65], v[150:153], v[182:185], v[62:65]
	v_mfma_f32_16x16x32_bf16 v[58:61], v[158:161], v[182:185], v[58:61]
	v_mfma_f32_16x16x32_bf16 v[50:53], v[150:153], v[190:193], v[50:53]
	v_mfma_f32_16x16x32_bf16 v[42:45], v[158:161], v[190:193], v[42:45]
	v_mfma_f32_16x16x32_bf16 v[34:37], v[150:153], v[206:209], v[34:37]
	v_mfma_f32_16x16x32_bf16 v[26:29], v[158:161], v[206:209], v[26:29]
	v_mfma_f32_16x16x32_bf16 v[18:21], v[150:153], v[214:217], v[18:21]
	v_mfma_f32_16x16x32_bf16 v[10:13], v[158:161], v[214:217], v[10:13]
	v_mfma_f32_16x16x32_bf16 v[62:65], v[154:157], v[186:189], v[62:65]
	v_mfma_f32_16x16x32_bf16 v[58:61], v[162:165], v[186:189], v[58:61]
	v_mfma_f32_16x16x32_bf16 v[50:53], v[154:157], v[202:205], v[50:53]
	v_mfma_f32_16x16x32_bf16 v[42:45], v[162:165], v[202:205], v[42:45]
	v_mfma_f32_16x16x32_bf16 v[34:37], v[154:157], v[210:213], v[34:37]
	v_mfma_f32_16x16x32_bf16 v[26:29], v[162:165], v[210:213], v[26:29]
	v_mfma_f32_16x16x32_bf16 v[18:21], v[154:157], v[218:221], v[18:21]
	v_mfma_f32_16x16x32_bf16 v[10:13], v[162:165], v[218:221], v[10:13]
	v_mfma_f32_16x16x32_bf16 v[54:57], v[166:169], v[182:185], v[54:57]
	v_mfma_f32_16x16x32_bf16 v[46:49], v[174:177], v[182:185], v[46:49]
	v_mfma_f32_16x16x32_bf16 v[38:41], v[166:169], v[190:193], v[38:41]
	v_mfma_f32_16x16x32_bf16 v[30:33], v[174:177], v[190:193], v[30:33]
	v_mfma_f32_16x16x32_bf16 v[22:25], v[166:169], v[206:209], v[22:25]
	v_mfma_f32_16x16x32_bf16 v[14:17], v[174:177], v[206:209], v[14:17]
	v_mfma_f32_16x16x32_bf16 v[6:9], v[166:169], v[214:217], v[6:9]
	v_mfma_f32_16x16x32_bf16 v[2:5], v[174:177], v[214:217], v[2:5]
	v_mfma_f32_16x16x32_bf16 v[54:57], v[170:173], v[186:189], v[54:57]
	v_mfma_f32_16x16x32_bf16 v[46:49], v[178:181], v[186:189], v[46:49]
	v_mfma_f32_16x16x32_bf16 v[38:41], v[170:173], v[202:205], v[38:41]
	v_mfma_f32_16x16x32_bf16 v[30:33], v[178:181], v[202:205], v[30:33]
	v_mfma_f32_16x16x32_bf16 v[22:25], v[170:173], v[210:213], v[22:25]
	v_mfma_f32_16x16x32_bf16 v[14:17], v[178:181], v[210:213], v[14:17]
	v_mfma_f32_16x16x32_bf16 v[6:9], v[170:173], v[218:221], v[6:9]
	v_mfma_f32_16x16x32_bf16 v[2:5], v[178:181], v[218:221], v[2:5]
	s_barrier
	s_setprio 0
	s_add_i32 s53, 0, 0x18000
	v_add_u32_e32 v142, s53, v147
	s_add_i32 s67, 0, 0x1c000
	ds_read_b128 v[150:153], v142
	ds_read_b128 v[154:157], v142 offset:1024
	ds_read_b128 v[158:161], v142 offset:2048
	ds_read_b128 v[162:165], v142 offset:3072
	v_add_u32_e32 v142, s67, v147
	ds_read_b128 v[166:169], v142
	ds_read_b128 v[170:173], v142 offset:1024
	ds_read_b128 v[174:177], v142 offset:2048
	ds_read_b128 v[178:181], v142 offset:3072
	s_add_u32 s54, s54, 0x40000
	s_addc_u32 s55, s55, 0
	s_mov_b32 m0, s61
	v_lshl_add_u64 v[236:237], s[54:55], 0, v[136:137]
	ds_read_b128 v[182:185], v149 offset:32768
	ds_read_b128 v[186:189], v149 offset:33792
	ds_read_b128 v[190:193], v149 offset:34816
	ds_read_b128 v[202:205], v149 offset:35840
	ds_read_b128 v[206:209], v149 offset:36864
	ds_read_b128 v[210:213], v149 offset:37888
	ds_read_b128 v[214:217], v149 offset:38912
	ds_read_b128 v[218:221], v149 offset:39936
	global_load_lds_dwordx4 v[236:237], off
	v_lshl_add_u64 v[236:237], s[54:55], 0, v[132:133]
	s_mov_b32 m0, s62
	s_nop 0
	global_load_lds_dwordx4 v[236:237], off
	s_waitcnt vmcnt(8)
	s_waitcnt lgkmcnt(0)
	s_setprio 1
	s_barrier
	v_mfma_f32_16x16x32_bf16 v[126:129], v[150:153], v[182:185], v[126:129]
	v_mfma_f32_16x16x32_bf16 v[122:125], v[158:161], v[182:185], v[122:125]
	v_mfma_f32_16x16x32_bf16 v[110:113], v[150:153], v[190:193], v[110:113]
	v_mfma_f32_16x16x32_bf16 v[106:109], v[158:161], v[190:193], v[106:109]
	v_mfma_f32_16x16x32_bf16 v[94:97], v[150:153], v[206:209], v[94:97]
	v_mfma_f32_16x16x32_bf16 v[90:93], v[158:161], v[206:209], v[90:93]
	v_mfma_f32_16x16x32_bf16 v[78:81], v[150:153], v[214:217], v[78:81]
	v_mfma_f32_16x16x32_bf16 v[74:77], v[158:161], v[214:217], v[74:77]
	v_mfma_f32_16x16x32_bf16 v[126:129], v[154:157], v[186:189], v[126:129]
	v_mfma_f32_16x16x32_bf16 v[122:125], v[162:165], v[186:189], v[122:125]
	v_mfma_f32_16x16x32_bf16 v[110:113], v[154:157], v[202:205], v[110:113]
	v_mfma_f32_16x16x32_bf16 v[106:109], v[162:165], v[202:205], v[106:109]
	v_mfma_f32_16x16x32_bf16 v[94:97], v[154:157], v[210:213], v[94:97]
	v_mfma_f32_16x16x32_bf16 v[90:93], v[162:165], v[210:213], v[90:93]
	v_mfma_f32_16x16x32_bf16 v[78:81], v[154:157], v[218:221], v[78:81]
	v_mfma_f32_16x16x32_bf16 v[74:77], v[162:165], v[218:221], v[74:77]
	v_mfma_f32_16x16x32_bf16 v[118:121], v[166:169], v[182:185], v[118:121]
	v_mfma_f32_16x16x32_bf16 v[114:117], v[174:177], v[182:185], v[114:117]
	v_mfma_f32_16x16x32_bf16 v[102:105], v[166:169], v[190:193], v[102:105]
	v_mfma_f32_16x16x32_bf16 v[98:101], v[174:177], v[190:193], v[98:101]
	v_mfma_f32_16x16x32_bf16 v[86:89], v[166:169], v[206:209], v[86:89]
	v_mfma_f32_16x16x32_bf16 v[82:85], v[174:177], v[206:209], v[82:85]
	v_mfma_f32_16x16x32_bf16 v[70:73], v[166:169], v[214:217], v[70:73]
	v_mfma_f32_16x16x32_bf16 v[66:69], v[174:177], v[214:217], v[66:69]
	v_mfma_f32_16x16x32_bf16 v[118:121], v[170:173], v[186:189], v[118:121]
	v_mfma_f32_16x16x32_bf16 v[114:117], v[178:181], v[186:189], v[114:117]
	v_mfma_f32_16x16x32_bf16 v[102:105], v[170:173], v[202:205], v[102:105]
	v_mfma_f32_16x16x32_bf16 v[98:101], v[178:181], v[202:205], v[98:101]
	v_mfma_f32_16x16x32_bf16 v[86:89], v[170:173], v[210:213], v[86:89]
	v_mfma_f32_16x16x32_bf16 v[82:85], v[178:181], v[210:213], v[82:85]
	v_mfma_f32_16x16x32_bf16 v[70:73], v[170:173], v[218:221], v[70:73]
	v_mfma_f32_16x16x32_bf16 v[66:69], v[178:181], v[218:221], v[66:69]
	s_barrier
	s_setprio 0
	s_add_i32 s53, s53, s58
	v_lshl_add_u64 v[144:145], v[144:145], 0, s[10:11]
	s_mov_b32 m0, s53
	ds_read_b128 v[182:185], v149 offset:49152
	ds_read_b128 v[186:189], v149 offset:50176
	ds_read_b128 v[190:193], v149 offset:51200
	ds_read_b128 v[202:205], v149 offset:52224
	ds_read_b128 v[206:209], v149 offset:53248
	ds_read_b128 v[210:213], v149 offset:54272
	ds_read_b128 v[214:217], v149 offset:55296
	ds_read_b128 v[218:221], v149 offset:56320
	s_add_i32 s49, s49, 2
	s_add_u32 s37, s37, 0x100
	s_addc_u32 s47, s47, 0
	s_add_u32 s4, s4, 0x100
	s_addc_u32 s5, s5, 0
	global_load_lds_dwordx4 v[144:145], off
	s_add_i32 m0, s53, 0x2000
	s_add_u32 s14, s14, 0x40080
	v_lshl_add_u64 v[144:145], v[222:223], 0, s[10:11]
	s_addc_u32 s15, s15, 0
	s_add_i32 s53, s67, s58
	global_load_lds_dwordx4 v[144:145], off
	v_lshl_add_u64 v[144:145], s[14:15], 0, v[134:135]
	s_mov_b32 m0, s53
	s_nop 0
	global_load_lds_dwordx4 v[144:145], off
	v_lshl_add_u64 v[144:145], s[14:15], 0, v[130:131]
	s_add_i32 m0, s53, 0x2000
	s_nop 0
	global_load_lds_dwordx4 v[144:145], off
	v_lshl_add_u64 v[144:145], v[232:233], 0, s[10:11]
	s_mov_b32 m0, s65
	s_nop 0
	global_load_lds_dwordx4 v[144:145], off
	v_lshl_add_u64 v[144:145], v[234:235], 0, s[10:11]
	s_mov_b32 m0, s66
	s_nop 0
	global_load_lds_dwordx4 v[144:145], off
	s_waitcnt vmcnt(8)
	s_waitcnt lgkmcnt(0)
	s_setprio 1
	s_barrier
	v_mfma_f32_16x16x32_bf16 v[62:65], v[150:153], v[182:185], v[62:65]
	v_mfma_f32_16x16x32_bf16 v[58:61], v[158:161], v[182:185], v[58:61]
	v_mfma_f32_16x16x32_bf16 v[50:53], v[150:153], v[190:193], v[50:53]
	v_mfma_f32_16x16x32_bf16 v[42:45], v[158:161], v[190:193], v[42:45]
	v_mfma_f32_16x16x32_bf16 v[34:37], v[150:153], v[206:209], v[34:37]
	v_mfma_f32_16x16x32_bf16 v[26:29], v[158:161], v[206:209], v[26:29]
	v_mfma_f32_16x16x32_bf16 v[18:21], v[150:153], v[214:217], v[18:21]
	v_mfma_f32_16x16x32_bf16 v[10:13], v[158:161], v[214:217], v[10:13]
	v_mfma_f32_16x16x32_bf16 v[62:65], v[154:157], v[186:189], v[62:65]
	v_mfma_f32_16x16x32_bf16 v[58:61], v[162:165], v[186:189], v[58:61]
	v_mfma_f32_16x16x32_bf16 v[50:53], v[154:157], v[202:205], v[50:53]
	v_mfma_f32_16x16x32_bf16 v[42:45], v[162:165], v[202:205], v[42:45]
	v_mfma_f32_16x16x32_bf16 v[34:37], v[154:157], v[210:213], v[34:37]
	v_mfma_f32_16x16x32_bf16 v[26:29], v[162:165], v[210:213], v[26:29]
	v_mfma_f32_16x16x32_bf16 v[18:21], v[154:157], v[218:221], v[18:21]
	v_mfma_f32_16x16x32_bf16 v[10:13], v[162:165], v[218:221], v[10:13]
	v_mfma_f32_16x16x32_bf16 v[54:57], v[166:169], v[182:185], v[54:57]
	v_mfma_f32_16x16x32_bf16 v[46:49], v[174:177], v[182:185], v[46:49]
	v_mfma_f32_16x16x32_bf16 v[38:41], v[166:169], v[190:193], v[38:41]
	v_mfma_f32_16x16x32_bf16 v[30:33], v[174:177], v[190:193], v[30:33]
	v_mfma_f32_16x16x32_bf16 v[22:25], v[166:169], v[206:209], v[22:25]
	v_mfma_f32_16x16x32_bf16 v[14:17], v[174:177], v[206:209], v[14:17]
	v_mfma_f32_16x16x32_bf16 v[6:9], v[166:169], v[214:217], v[6:9]
	v_mfma_f32_16x16x32_bf16 v[2:5], v[174:177], v[214:217], v[2:5]
	v_mfma_f32_16x16x32_bf16 v[54:57], v[170:173], v[186:189], v[54:57]
	v_mfma_f32_16x16x32_bf16 v[46:49], v[178:181], v[186:189], v[46:49]
	v_mfma_f32_16x16x32_bf16 v[38:41], v[170:173], v[202:205], v[38:41]
	v_mfma_f32_16x16x32_bf16 v[30:33], v[178:181], v[202:205], v[30:33]
	v_mfma_f32_16x16x32_bf16 v[22:25], v[170:173], v[210:213], v[22:25]
	v_mfma_f32_16x16x32_bf16 v[14:17], v[178:181], v[210:213], v[14:17]
	v_mfma_f32_16x16x32_bf16 v[6:9], v[170:173], v[218:221], v[6:9]
	v_mfma_f32_16x16x32_bf16 v[2:5], v[178:181], v[218:221], v[2:5]
	s_barrier
	s_setprio 0
	s_cmp_gt_u32 s49, 13
	s_cbranch_scc0 .LBB0_183
	s_and_b64 vcc, exec, s[44:45]
	s_cbranch_vccz .LBB0_186
	s_barrier

.LBB0_481:
	s_add_i32 s70, 0, 0x10000
	s_add_i32 s72, 0, 0x14000
	v_add_u32_e32 v134, s70, v183
	v_add_u32_e32 v168, s72, v183
	ds_read_b128 v[114:117], v134
	ds_read_b128 v[118:121], v134 offset:1024
	ds_read_b128 v[122:125], v134 offset:2048
	ds_read_b128 v[134:137], v134 offset:3072
	ds_read_b128 v[146:149], v168
	ds_read_b128 v[150:153], v168 offset:1024
	ds_read_b128 v[164:167], v168 offset:2048
	ds_read_b128 v[168:171], v168 offset:3072
	v_lshl_add_u64 v[180:181], s[12:13], 0, v[162:163]
	s_add_i32 m0, s63, 0xc000
	ds_read_b128 v[172:175], v185
	ds_read_b128 v[176:179], v185 offset:1024
	ds_read_b128 v[186:189], v185 offset:2048
	ds_read_b128 v[190:193], v185 offset:3072
	ds_read_b128 v[202:205], v185 offset:4096
	ds_read_b128 v[206:209], v185 offset:5120
	ds_read_b128 v[210:213], v185 offset:6144
	ds_read_b128 v[214:217], v185 offset:7168
	s_add_u32 s14, s12, 0xfffc0080
	s_addc_u32 s15, s13, -1
	s_cmp_eq_u32 s53, 12
	s_cselect_b32 s59, s28, s15
	s_cselect_b32 s58, s29, s14
	s_cselect_b32 s15, s33, s51
	s_cselect_b32 s14, s36, s37
	global_load_lds_dwordx4 v[180:181], off
	v_lshl_add_u64 v[180:181], s[12:13], 0, v[160:161]
	s_add_i32 m0, s63, 0xe000
	s_nop 0
	global_load_lds_dwordx4 v[180:181], off
	s_waitcnt vmcnt(8)
	s_waitcnt lgkmcnt(0)
	s_setprio 1
	s_barrier
	v_mfma_f32_16x16x32_bf16 v[142:145], v[114:117], v[172:175], v[142:145]
	v_mfma_f32_16x16x32_bf16 v[138:141], v[122:125], v[172:175], v[138:141]
	v_mfma_f32_16x16x32_bf16 v[110:113], v[114:117], v[186:189], v[110:113]
	v_mfma_f32_16x16x32_bf16 v[106:109], v[122:125], v[186:189], v[106:109]
	v_mfma_f32_16x16x32_bf16 v[94:97], v[114:117], v[202:205], v[94:97]
	v_mfma_f32_16x16x32_bf16 v[90:93], v[122:125], v[202:205], v[90:93]
	v_mfma_f32_16x16x32_bf16 v[78:81], v[114:117], v[210:213], v[78:81]
	v_mfma_f32_16x16x32_bf16 v[74:77], v[122:125], v[210:213], v[74:77]
	v_mfma_f32_16x16x32_bf16 v[142:145], v[118:121], v[176:179], v[142:145]
	v_mfma_f32_16x16x32_bf16 v[138:141], v[134:137], v[176:179], v[138:141]
	v_mfma_f32_16x16x32_bf16 v[110:113], v[118:121], v[190:193], v[110:113]
	v_mfma_f32_16x16x32_bf16 v[106:109], v[134:137], v[190:193], v[106:109]
	v_mfma_f32_16x16x32_bf16 v[94:97], v[118:121], v[206:209], v[94:97]
	v_mfma_f32_16x16x32_bf16 v[90:93], v[134:137], v[206:209], v[90:93]
	v_mfma_f32_16x16x32_bf16 v[78:81], v[118:121], v[214:217], v[78:81]
	v_mfma_f32_16x16x32_bf16 v[74:77], v[134:137], v[214:217], v[74:77]
	v_mfma_f32_16x16x32_bf16 v[130:133], v[146:149], v[172:175], v[130:133]
	v_mfma_f32_16x16x32_bf16 v[126:129], v[164:167], v[172:175], v[126:129]
	v_mfma_f32_16x16x32_bf16 v[102:105], v[146:149], v[186:189], v[102:105]
	v_mfma_f32_16x16x32_bf16 v[98:101], v[164:167], v[186:189], v[98:101]
	v_mfma_f32_16x16x32_bf16 v[86:89], v[146:149], v[202:205], v[86:89]
	v_mfma_f32_16x16x32_bf16 v[82:85], v[164:167], v[202:205], v[82:85]
	v_mfma_f32_16x16x32_bf16 v[70:73], v[146:149], v[210:213], v[70:73]
	v_mfma_f32_16x16x32_bf16 v[66:69], v[164:167], v[210:213], v[66:69]
	v_mfma_f32_16x16x32_bf16 v[130:133], v[150:153], v[176:179], v[130:133]
	v_mfma_f32_16x16x32_bf16 v[126:129], v[168:171], v[176:179], v[126:129]
	v_mfma_f32_16x16x32_bf16 v[102:105], v[150:153], v[190:193], v[102:105]
	v_mfma_f32_16x16x32_bf16 v[98:101], v[168:171], v[190:193], v[98:101]
	v_mfma_f32_16x16x32_bf16 v[86:89], v[150:153], v[206:209], v[86:89]
	v_mfma_f32_16x16x32_bf16 v[82:85], v[168:171], v[206:209], v[82:85]
	v_mfma_f32_16x16x32_bf16 v[70:73], v[150:153], v[214:217], v[70:73]
	v_mfma_f32_16x16x32_bf16 v[66:69], v[168:171], v[214:217], v[66:69]
	s_barrier
	s_setprio 0
	s_add_i32 s70, s70, s62
	v_lshl_add_u64 v[180:181], s[14:15], 0, v[0:1]
	s_mov_b32 m0, s70
	ds_read_b128 v[172:175], v185 offset:16384
	ds_read_b128 v[176:179], v185 offset:17408
	ds_read_b128 v[186:189], v185 offset:18432
	ds_read_b128 v[190:193], v185 offset:19456
	ds_read_b128 v[202:205], v185 offset:20480
	ds_read_b128 v[206:209], v185 offset:21504
	ds_read_b128 v[210:213], v185 offset:22528
	ds_read_b128 v[214:217], v185 offset:23552
	global_load_lds_dwordx4 v[180:181], off
	s_add_i32 m0, s70, 0x2000
	s_add_u32 s70, s14, 0x40000
	v_lshl_add_u64 v[218:219], s[14:15], 0, v[154:155]
	s_addc_u32 s71, s15, 0
	s_add_i32 s72, s72, s62
	global_load_lds_dwordx4 v[218:219], off
	v_lshl_add_u64 v[220:221], s[70:71], 0, v[0:1]
	s_mov_b32 m0, s72
	v_lshl_add_u64 v[222:223], s[58:59], 0, v[156:157]
	global_load_lds_dwordx4 v[220:221], off
	v_lshl_add_u64 v[220:221], s[70:71], 0, v[154:155]
	s_add_i32 m0, s72, 0x2000
	s_nop 0
	global_load_lds_dwordx4 v[220:221], off
	v_lshl_add_u64 v[220:221], s[58:59], 0, v[158:159]
	s_mov_b32 m0, s63
	s_nop 0
	global_load_lds_dwordx4 v[220:221], off
	s_mov_b32 m0, s64
	s_nop 0
	global_load_lds_dwordx4 v[222:223], off
	s_waitcnt vmcnt(8)
	s_waitcnt lgkmcnt(0)
	s_setprio 1
	s_barrier
	v_mfma_f32_16x16x32_bf16 v[62:65], v[114:117], v[172:175], v[62:65]
	v_mfma_f32_16x16x32_bf16 v[58:61], v[122:125], v[172:175], v[58:61]
	v_mfma_f32_16x16x32_bf16 v[46:49], v[114:117], v[186:189], v[46:49]
	v_mfma_f32_16x16x32_bf16 v[42:45], v[122:125], v[186:189], v[42:45]
	v_mfma_f32_16x16x32_bf16 v[30:33], v[114:117], v[202:205], v[30:33]
	v_mfma_f32_16x16x32_bf16 v[26:29], v[122:125], v[202:205], v[26:29]
	v_mfma_f32_16x16x32_bf16 v[14:17], v[114:117], v[210:213], v[14:17]
	v_mfma_f32_16x16x32_bf16 v[10:13], v[122:125], v[210:213], v[10:13]
	v_mfma_f32_16x16x32_bf16 v[62:65], v[118:121], v[176:179], v[62:65]
	v_mfma_f32_16x16x32_bf16 v[58:61], v[134:137], v[176:179], v[58:61]
	v_mfma_f32_16x16x32_bf16 v[46:49], v[118:121], v[190:193], v[46:49]
	v_mfma_f32_16x16x32_bf16 v[42:45], v[134:137], v[190:193], v[42:45]
	v_mfma_f32_16x16x32_bf16 v[30:33], v[118:121], v[206:209], v[30:33]
	v_mfma_f32_16x16x32_bf16 v[26:29], v[134:137], v[206:209], v[26:29]
	v_mfma_f32_16x16x32_bf16 v[14:17], v[118:121], v[214:217], v[14:17]
	v_mfma_f32_16x16x32_bf16 v[10:13], v[134:137], v[214:217], v[10:13]
	v_mfma_f32_16x16x32_bf16 v[54:57], v[146:149], v[172:175], v[54:57]
	v_mfma_f32_16x16x32_bf16 v[50:53], v[164:167], v[172:175], v[50:53]
	v_mfma_f32_16x16x32_bf16 v[38:41], v[146:149], v[186:189], v[38:41]
	v_mfma_f32_16x16x32_bf16 v[34:37], v[164:167], v[186:189], v[34:37]
	v_mfma_f32_16x16x32_bf16 v[22:25], v[146:149], v[202:205], v[22:25]
	v_mfma_f32_16x16x32_bf16 v[18:21], v[164:167], v[202:205], v[18:21]
	v_mfma_f32_16x16x32_bf16 v[6:9], v[146:149], v[210:213], v[6:9]
	v_mfma_f32_16x16x32_bf16 v[2:5], v[164:167], v[210:213], v[2:5]
	v_mfma_f32_16x16x32_bf16 v[54:57], v[150:153], v[176:179], v[54:57]
	v_mfma_f32_16x16x32_bf16 v[50:53], v[168:171], v[176:179], v[50:53]
	v_mfma_f32_16x16x32_bf16 v[38:41], v[150:153], v[190:193], v[38:41]
	v_mfma_f32_16x16x32_bf16 v[34:37], v[168:171], v[190:193], v[34:37]
	v_mfma_f32_16x16x32_bf16 v[22:25], v[150:153], v[206:209], v[22:25]
	v_mfma_f32_16x16x32_bf16 v[18:21], v[168:171], v[206:209], v[18:21]
	v_mfma_f32_16x16x32_bf16 v[6:9], v[150:153], v[214:217], v[6:9]
	v_mfma_f32_16x16x32_bf16 v[2:5], v[168:171], v[214:217], v[2:5]
	s_barrier
	s_setprio 0
	s_add_i32 s70, 0, 0x18000
	s_add_i32 s71, 0, 0x1c000
	v_add_u32_e32 v134, s70, v183
	v_add_u32_e32 v168, s71, v183
	ds_read_b128 v[114:117], v134
	ds_read_b128 v[118:121], v134 offset:1024
	ds_read_b128 v[122:125], v134 offset:2048
	ds_read_b128 v[134:137], v134 offset:3072
	ds_read_b128 v[146:149], v168
	ds_read_b128 v[150:153], v168 offset:1024
	ds_read_b128 v[164:167], v168 offset:2048
	ds_read_b128 v[168:171], v168 offset:3072
	s_add_u32 s58, s58, 0x40000
	s_addc_u32 s59, s59, 0
	s_mov_b32 m0, s65
	v_lshl_add_u64 v[232:233], s[58:59], 0, v[158:159]
	ds_read_b128 v[172:175], v185 offset:32768
	ds_read_b128 v[176:179], v185 offset:33792
	ds_read_b128 v[186:189], v185 offset:34816
	ds_read_b128 v[190:193], v185 offset:35840
	ds_read_b128 v[202:205], v185 offset:36864
	ds_read_b128 v[206:209], v185 offset:37888
	ds_read_b128 v[210:213], v185 offset:38912
	ds_read_b128 v[214:217], v185 offset:39936
	global_load_lds_dwordx4 v[232:233], off
	v_lshl_add_u64 v[232:233], s[58:59], 0, v[156:157]
	s_mov_b32 m0, s66
	s_nop 0
	global_load_lds_dwordx4 v[232:233], off
	s_waitcnt vmcnt(8)
	s_waitcnt lgkmcnt(0)
	s_setprio 1
	s_barrier
	v_mfma_f32_16x16x32_bf16 v[142:145], v[114:117], v[172:175], v[142:145]
	v_mfma_f32_16x16x32_bf16 v[138:141], v[122:125], v[172:175], v[138:141]
	v_mfma_f32_16x16x32_bf16 v[110:113], v[114:117], v[186:189], v[110:113]
	v_mfma_f32_16x16x32_bf16 v[106:109], v[122:125], v[186:189], v[106:109]
	v_mfma_f32_16x16x32_bf16 v[94:97], v[114:117], v[202:205], v[94:97]
	v_mfma_f32_16x16x32_bf16 v[90:93], v[122:125], v[202:205], v[90:93]
	v_mfma_f32_16x16x32_bf16 v[78:81], v[114:117], v[210:213], v[78:81]
	v_mfma_f32_16x16x32_bf16 v[74:77], v[122:125], v[210:213], v[74:77]
	v_mfma_f32_16x16x32_bf16 v[142:145], v[118:121], v[176:179], v[142:145]
	v_mfma_f32_16x16x32_bf16 v[138:141], v[134:137], v[176:179], v[138:141]
	v_mfma_f32_16x16x32_bf16 v[110:113], v[118:121], v[190:193], v[110:113]
	v_mfma_f32_16x16x32_bf16 v[106:109], v[134:137], v[190:193], v[106:109]
	v_mfma_f32_16x16x32_bf16 v[94:97], v[118:121], v[206:209], v[94:97]
	v_mfma_f32_16x16x32_bf16 v[90:93], v[134:137], v[206:209], v[90:93]
	v_mfma_f32_16x16x32_bf16 v[78:81], v[118:121], v[214:217], v[78:81]
	v_mfma_f32_16x16x32_bf16 v[74:77], v[134:137], v[214:217], v[74:77]
	v_mfma_f32_16x16x32_bf16 v[130:133], v[146:149], v[172:175], v[130:133]
	v_mfma_f32_16x16x32_bf16 v[126:129], v[164:167], v[172:175], v[126:129]
	v_mfma_f32_16x16x32_bf16 v[102:105], v[146:149], v[186:189], v[102:105]
	v_mfma_f32_16x16x32_bf16 v[98:101], v[164:167], v[186:189], v[98:101]
	v_mfma_f32_16x16x32_bf16 v[86:89], v[146:149], v[202:205], v[86:89]
	v_mfma_f32_16x16x32_bf16 v[82:85], v[164:167], v[202:205], v[82:85]
	v_mfma_f32_16x16x32_bf16 v[70:73], v[146:149], v[210:213], v[70:73]
	v_mfma_f32_16x16x32_bf16 v[66:69], v[164:167], v[210:213], v[66:69]
	v_mfma_f32_16x16x32_bf16 v[130:133], v[150:153], v[176:179], v[130:133]
	v_mfma_f32_16x16x32_bf16 v[126:129], v[168:171], v[176:179], v[126:129]
	v_mfma_f32_16x16x32_bf16 v[102:105], v[150:153], v[190:193], v[102:105]
	v_mfma_f32_16x16x32_bf16 v[98:101], v[168:171], v[190:193], v[98:101]
	v_mfma_f32_16x16x32_bf16 v[86:89], v[150:153], v[206:209], v[86:89]
	v_mfma_f32_16x16x32_bf16 v[82:85], v[168:171], v[206:209], v[82:85]
	v_mfma_f32_16x16x32_bf16 v[70:73], v[150:153], v[214:217], v[70:73]
	v_mfma_f32_16x16x32_bf16 v[66:69], v[168:171], v[214:217], v[66:69]
	s_barrier
	s_setprio 0
	s_add_i32 s58, s70, s62
	v_lshl_add_u64 v[180:181], v[180:181], 0, s[10:11]
	s_mov_b32 m0, s58
	ds_read_b128 v[172:175], v185 offset:49152
	ds_read_b128 v[176:179], v185 offset:50176
	ds_read_b128 v[186:189], v185 offset:51200
	ds_read_b128 v[190:193], v185 offset:52224
	ds_read_b128 v[202:205], v185 offset:53248
	ds_read_b128 v[206:209], v185 offset:54272
	ds_read_b128 v[210:213], v185 offset:55296
	ds_read_b128 v[214:217], v185 offset:56320
	s_add_i32 s53, s53, 2
	s_add_u32 s37, s37, 0x100
	s_addc_u32 s51, s51, 0
	s_add_u32 s12, s12, 0x100
	s_addc_u32 s13, s13, 0
	global_load_lds_dwordx4 v[180:181], off
	s_add_i32 m0, s58, 0x2000
	s_add_u32 s14, s14, 0x40080
	v_lshl_add_u64 v[180:181], v[218:219], 0, s[10:11]
	s_addc_u32 s15, s15, 0
	s_add_i32 s58, s71, s62
	global_load_lds_dwordx4 v[180:181], off
	v_lshl_add_u64 v[180:181], s[14:15], 0, v[0:1]
	s_mov_b32 m0, s58
	s_nop 0
	global_load_lds_dwordx4 v[180:181], off
	v_lshl_add_u64 v[180:181], s[14:15], 0, v[154:155]
	s_add_i32 m0, s58, 0x2000
	s_nop 0
	global_load_lds_dwordx4 v[180:181], off
	v_lshl_add_u64 v[180:181], v[220:221], 0, s[10:11]
	s_mov_b32 m0, s67
	s_nop 0
	global_load_lds_dwordx4 v[180:181], off
	v_lshl_add_u64 v[180:181], v[222:223], 0, s[10:11]
	s_mov_b32 m0, s68
	s_nop 0
	global_load_lds_dwordx4 v[180:181], off
	s_waitcnt vmcnt(8)
	s_waitcnt lgkmcnt(0)
	s_setprio 1
	s_barrier
	v_mfma_f32_16x16x32_bf16 v[62:65], v[114:117], v[172:175], v[62:65]
	v_mfma_f32_16x16x32_bf16 v[58:61], v[122:125], v[172:175], v[58:61]
	v_mfma_f32_16x16x32_bf16 v[46:49], v[114:117], v[186:189], v[46:49]
	v_mfma_f32_16x16x32_bf16 v[42:45], v[122:125], v[186:189], v[42:45]
	v_mfma_f32_16x16x32_bf16 v[30:33], v[114:117], v[202:205], v[30:33]
	v_mfma_f32_16x16x32_bf16 v[26:29], v[122:125], v[202:205], v[26:29]
	v_mfma_f32_16x16x32_bf16 v[14:17], v[114:117], v[210:213], v[14:17]
	v_mfma_f32_16x16x32_bf16 v[10:13], v[122:125], v[210:213], v[10:13]
	v_mfma_f32_16x16x32_bf16 v[62:65], v[118:121], v[176:179], v[62:65]
	v_mfma_f32_16x16x32_bf16 v[58:61], v[134:137], v[176:179], v[58:61]
	v_mfma_f32_16x16x32_bf16 v[46:49], v[118:121], v[190:193], v[46:49]
	v_mfma_f32_16x16x32_bf16 v[42:45], v[134:137], v[190:193], v[42:45]
	v_mfma_f32_16x16x32_bf16 v[30:33], v[118:121], v[206:209], v[30:33]
	v_mfma_f32_16x16x32_bf16 v[26:29], v[134:137], v[206:209], v[26:29]
	v_mfma_f32_16x16x32_bf16 v[14:17], v[118:121], v[214:217], v[14:17]
	v_mfma_f32_16x16x32_bf16 v[10:13], v[134:137], v[214:217], v[10:13]
	v_mfma_f32_16x16x32_bf16 v[54:57], v[146:149], v[172:175], v[54:57]
	v_mfma_f32_16x16x32_bf16 v[50:53], v[164:167], v[172:175], v[50:53]
	v_mfma_f32_16x16x32_bf16 v[38:41], v[146:149], v[186:189], v[38:41]
	v_mfma_f32_16x16x32_bf16 v[34:37], v[164:167], v[186:189], v[34:37]
	v_mfma_f32_16x16x32_bf16 v[22:25], v[146:149], v[202:205], v[22:25]
	v_mfma_f32_16x16x32_bf16 v[18:21], v[164:167], v[202:205], v[18:21]
	v_mfma_f32_16x16x32_bf16 v[6:9], v[146:149], v[210:213], v[6:9]
	v_mfma_f32_16x16x32_bf16 v[2:5], v[164:167], v[210:213], v[2:5]
	v_mfma_f32_16x16x32_bf16 v[54:57], v[150:153], v[176:179], v[54:57]
	v_mfma_f32_16x16x32_bf16 v[50:53], v[168:171], v[176:179], v[50:53]
	v_mfma_f32_16x16x32_bf16 v[38:41], v[150:153], v[190:193], v[38:41]
	v_mfma_f32_16x16x32_bf16 v[34:37], v[168:171], v[190:193], v[34:37]
	v_mfma_f32_16x16x32_bf16 v[22:25], v[150:153], v[206:209], v[22:25]
	v_mfma_f32_16x16x32_bf16 v[18:21], v[168:171], v[206:209], v[18:21]
	v_mfma_f32_16x16x32_bf16 v[6:9], v[150:153], v[214:217], v[6:9]
	v_mfma_f32_16x16x32_bf16 v[2:5], v[168:171], v[214:217], v[2:5]
	s_barrier
	s_setprio 0
	s_cmp_gt_u32 s53, 13
	s_cbranch_scc0 .LBB0_481
	s_and_b64 vcc, exec, s[48:49]
	s_cbranch_vccz .LBB0_484
	s_barrier

.LBB0_561:
	s_add_i32 s66, 0, 0x10000
	v_add_u32_e32 v140, s66, v145
	s_add_i32 s68, 0, 0x14000
	ds_read_b128 v[150:153], v140
	ds_read_b128 v[154:157], v140 offset:1024
	ds_read_b128 v[158:161], v140 offset:2048
	ds_read_b128 v[162:165], v140 offset:3072
	v_add_u32_e32 v140, s68, v145
	ds_read_b128 v[166:169], v140
	ds_read_b128 v[170:173], v140 offset:1024
	ds_read_b128 v[174:177], v140 offset:2048
	ds_read_b128 v[178:181], v140 offset:3072
	v_lshl_add_u64 v[142:143], s[12:13], 0, v[138:139]
	s_add_i32 m0, s59, 0xc000
	ds_read_b128 v[182:185], v149
	ds_read_b128 v[186:189], v149 offset:1024
	ds_read_b128 v[190:193], v149 offset:2048
	ds_read_b128 v[202:205], v149 offset:3072
	ds_read_b128 v[206:209], v149 offset:4096
	ds_read_b128 v[210:213], v149 offset:5120
	ds_read_b128 v[214:217], v149 offset:6144
	ds_read_b128 v[218:221], v149 offset:7168
	s_add_u32 s14, s12, 0xfffc0080
	s_addc_u32 s15, s13, -1
	s_cmp_eq_u32 s49, 12
	s_cselect_b32 s55, s28, s15
	s_cselect_b32 s54, s29, s14
	s_cselect_b32 s15, s33, s47
	s_cselect_b32 s14, s36, s37
	global_load_lds_dwordx4 v[142:143], off
	v_lshl_add_u64 v[142:143], s[12:13], 0, v[136:137]
	s_add_i32 m0, s59, 0xe000
	s_nop 0
	global_load_lds_dwordx4 v[142:143], off
	s_waitcnt vmcnt(8)
	s_waitcnt lgkmcnt(0)
	s_setprio 1
	s_barrier
	v_mfma_f32_16x16x32_bf16 v[126:129], v[150:153], v[182:185], v[126:129]
	v_mfma_f32_16x16x32_bf16 v[122:125], v[158:161], v[182:185], v[122:125]
	v_mfma_f32_16x16x32_bf16 v[110:113], v[150:153], v[190:193], v[110:113]
	v_mfma_f32_16x16x32_bf16 v[106:109], v[158:161], v[190:193], v[106:109]
	v_mfma_f32_16x16x32_bf16 v[94:97], v[150:153], v[206:209], v[94:97]
	v_mfma_f32_16x16x32_bf16 v[90:93], v[158:161], v[206:209], v[90:93]
	v_mfma_f32_16x16x32_bf16 v[78:81], v[150:153], v[214:217], v[78:81]
	v_mfma_f32_16x16x32_bf16 v[74:77], v[158:161], v[214:217], v[74:77]
	v_mfma_f32_16x16x32_bf16 v[126:129], v[154:157], v[186:189], v[126:129]
	v_mfma_f32_16x16x32_bf16 v[122:125], v[162:165], v[186:189], v[122:125]
	v_mfma_f32_16x16x32_bf16 v[110:113], v[154:157], v[202:205], v[110:113]
	v_mfma_f32_16x16x32_bf16 v[106:109], v[162:165], v[202:205], v[106:109]
	v_mfma_f32_16x16x32_bf16 v[94:97], v[154:157], v[210:213], v[94:97]
	v_mfma_f32_16x16x32_bf16 v[90:93], v[162:165], v[210:213], v[90:93]
	v_mfma_f32_16x16x32_bf16 v[78:81], v[154:157], v[218:221], v[78:81]
	v_mfma_f32_16x16x32_bf16 v[74:77], v[162:165], v[218:221], v[74:77]
	v_mfma_f32_16x16x32_bf16 v[118:121], v[166:169], v[182:185], v[118:121]
	v_mfma_f32_16x16x32_bf16 v[114:117], v[174:177], v[182:185], v[114:117]
	v_mfma_f32_16x16x32_bf16 v[102:105], v[166:169], v[190:193], v[102:105]
	v_mfma_f32_16x16x32_bf16 v[98:101], v[174:177], v[190:193], v[98:101]
	v_mfma_f32_16x16x32_bf16 v[86:89], v[166:169], v[206:209], v[86:89]
	v_mfma_f32_16x16x32_bf16 v[82:85], v[174:177], v[206:209], v[82:85]
	v_mfma_f32_16x16x32_bf16 v[70:73], v[166:169], v[214:217], v[70:73]
	v_mfma_f32_16x16x32_bf16 v[66:69], v[174:177], v[214:217], v[66:69]
	v_mfma_f32_16x16x32_bf16 v[118:121], v[170:173], v[186:189], v[118:121]
	v_mfma_f32_16x16x32_bf16 v[114:117], v[178:181], v[186:189], v[114:117]
	v_mfma_f32_16x16x32_bf16 v[102:105], v[170:173], v[202:205], v[102:105]
	v_mfma_f32_16x16x32_bf16 v[98:101], v[178:181], v[202:205], v[98:101]
	v_mfma_f32_16x16x32_bf16 v[86:89], v[170:173], v[210:213], v[86:89]
	v_mfma_f32_16x16x32_bf16 v[82:85], v[178:181], v[210:213], v[82:85]
	v_mfma_f32_16x16x32_bf16 v[70:73], v[170:173], v[218:221], v[70:73]
	v_mfma_f32_16x16x32_bf16 v[66:69], v[178:181], v[218:221], v[66:69]
	s_barrier
	s_setprio 0
	s_add_i32 s66, s66, s58
	v_lshl_add_u64 v[142:143], s[14:15], 0, v[0:1]
	s_mov_b32 m0, s66
	ds_read_b128 v[182:185], v149 offset:16384
	ds_read_b128 v[186:189], v149 offset:17408
	ds_read_b128 v[190:193], v149 offset:18432
	ds_read_b128 v[202:205], v149 offset:19456
	ds_read_b128 v[206:209], v149 offset:20480
	ds_read_b128 v[210:213], v149 offset:21504
	ds_read_b128 v[214:217], v149 offset:22528
	ds_read_b128 v[218:221], v149 offset:23552
	global_load_lds_dwordx4 v[142:143], off
	s_add_i32 m0, s66, 0x2000
	s_add_u32 s66, s14, 0x40000
	v_lshl_add_u64 v[222:223], s[14:15], 0, v[130:131]
	s_addc_u32 s67, s15, 0
	s_add_i32 s68, s68, s58
	global_load_lds_dwordx4 v[222:223], off
	v_lshl_add_u64 v[232:233], s[66:67], 0, v[0:1]
	s_mov_b32 m0, s68
	v_lshl_add_u64 v[234:235], s[54:55], 0, v[132:133]
	global_load_lds_dwordx4 v[232:233], off
	v_lshl_add_u64 v[232:233], s[66:67], 0, v[130:131]
	s_add_i32 m0, s68, 0x2000
	s_nop 0
	global_load_lds_dwordx4 v[232:233], off
	v_lshl_add_u64 v[232:233], s[54:55], 0, v[134:135]
	s_mov_b32 m0, s59
	s_nop 0
	global_load_lds_dwordx4 v[232:233], off
	s_mov_b32 m0, s60
	s_nop 0
	global_load_lds_dwordx4 v[234:235], off
	s_waitcnt vmcnt(8)
	s_waitcnt lgkmcnt(0)
	s_setprio 1
	s_barrier
	v_mfma_f32_16x16x32_bf16 v[62:65], v[150:153], v[182:185], v[62:65]
	v_mfma_f32_16x16x32_bf16 v[58:61], v[158:161], v[182:185], v[58:61]
	v_mfma_f32_16x16x32_bf16 v[46:49], v[150:153], v[190:193], v[46:49]
	v_mfma_f32_16x16x32_bf16 v[42:45], v[158:161], v[190:193], v[42:45]
	v_mfma_f32_16x16x32_bf16 v[30:33], v[150:153], v[206:209], v[30:33]
	v_mfma_f32_16x16x32_bf16 v[26:29], v[158:161], v[206:209], v[26:29]
	v_mfma_f32_16x16x32_bf16 v[14:17], v[150:153], v[214:217], v[14:17]
	v_mfma_f32_16x16x32_bf16 v[10:13], v[158:161], v[214:217], v[10:13]
	v_mfma_f32_16x16x32_bf16 v[62:65], v[154:157], v[186:189], v[62:65]
	v_mfma_f32_16x16x32_bf16 v[58:61], v[162:165], v[186:189], v[58:61]
	v_mfma_f32_16x16x32_bf16 v[46:49], v[154:157], v[202:205], v[46:49]
	v_mfma_f32_16x16x32_bf16 v[42:45], v[162:165], v[202:205], v[42:45]
	v_mfma_f32_16x16x32_bf16 v[30:33], v[154:157], v[210:213], v[30:33]
	v_mfma_f32_16x16x32_bf16 v[26:29], v[162:165], v[210:213], v[26:29]
	v_mfma_f32_16x16x32_bf16 v[14:17], v[154:157], v[218:221], v[14:17]
	v_mfma_f32_16x16x32_bf16 v[10:13], v[162:165], v[218:221], v[10:13]
	v_mfma_f32_16x16x32_bf16 v[54:57], v[166:169], v[182:185], v[54:57]
	v_mfma_f32_16x16x32_bf16 v[50:53], v[174:177], v[182:185], v[50:53]
	v_mfma_f32_16x16x32_bf16 v[38:41], v[166:169], v[190:193], v[38:41]
	v_mfma_f32_16x16x32_bf16 v[34:37], v[174:177], v[190:193], v[34:37]
	v_mfma_f32_16x16x32_bf16 v[22:25], v[166:169], v[206:209], v[22:25]
	v_mfma_f32_16x16x32_bf16 v[18:21], v[174:177], v[206:209], v[18:21]
	v_mfma_f32_16x16x32_bf16 v[6:9], v[166:169], v[214:217], v[6:9]
	v_mfma_f32_16x16x32_bf16 v[2:5], v[174:177], v[214:217], v[2:5]
	v_mfma_f32_16x16x32_bf16 v[54:57], v[170:173], v[186:189], v[54:57]
	v_mfma_f32_16x16x32_bf16 v[50:53], v[178:181], v[186:189], v[50:53]
	v_mfma_f32_16x16x32_bf16 v[38:41], v[170:173], v[202:205], v[38:41]
	v_mfma_f32_16x16x32_bf16 v[34:37], v[178:181], v[202:205], v[34:37]
	v_mfma_f32_16x16x32_bf16 v[22:25], v[170:173], v[210:213], v[22:25]
	v_mfma_f32_16x16x32_bf16 v[18:21], v[178:181], v[210:213], v[18:21]
	v_mfma_f32_16x16x32_bf16 v[6:9], v[170:173], v[218:221], v[6:9]
	v_mfma_f32_16x16x32_bf16 v[2:5], v[178:181], v[218:221], v[2:5]
	s_barrier
	s_setprio 0
	s_add_i32 s66, 0, 0x18000
	v_add_u32_e32 v140, s66, v145
	s_add_i32 s67, 0, 0x1c000
	ds_read_b128 v[150:153], v140
	ds_read_b128 v[154:157], v140 offset:1024
	ds_read_b128 v[158:161], v140 offset:2048
	ds_read_b128 v[162:165], v140 offset:3072
	v_add_u32_e32 v140, s67, v145
	ds_read_b128 v[166:169], v140
	ds_read_b128 v[170:173], v140 offset:1024
	ds_read_b128 v[174:177], v140 offset:2048
	ds_read_b128 v[178:181], v140 offset:3072
	s_add_u32 s54, s54, 0x40000
	s_addc_u32 s55, s55, 0
	s_mov_b32 m0, s61
	v_lshl_add_u64 v[236:237], s[54:55], 0, v[134:135]
	ds_read_b128 v[182:185], v149 offset:32768
	ds_read_b128 v[186:189], v149 offset:33792
	ds_read_b128 v[190:193], v149 offset:34816
	ds_read_b128 v[202:205], v149 offset:35840
	ds_read_b128 v[206:209], v149 offset:36864
	ds_read_b128 v[210:213], v149 offset:37888
	ds_read_b128 v[214:217], v149 offset:38912
	ds_read_b128 v[218:221], v149 offset:39936
	global_load_lds_dwordx4 v[236:237], off
	v_lshl_add_u64 v[236:237], s[54:55], 0, v[132:133]
	s_mov_b32 m0, s62
	s_nop 0
	global_load_lds_dwordx4 v[236:237], off
	s_waitcnt vmcnt(8)
	s_waitcnt lgkmcnt(0)
	s_setprio 1
	s_barrier
	v_mfma_f32_16x16x32_bf16 v[126:129], v[150:153], v[182:185], v[126:129]
	v_mfma_f32_16x16x32_bf16 v[122:125], v[158:161], v[182:185], v[122:125]
	v_mfma_f32_16x16x32_bf16 v[110:113], v[150:153], v[190:193], v[110:113]
	v_mfma_f32_16x16x32_bf16 v[106:109], v[158:161], v[190:193], v[106:109]
	v_mfma_f32_16x16x32_bf16 v[94:97], v[150:153], v[206:209], v[94:97]
	v_mfma_f32_16x16x32_bf16 v[90:93], v[158:161], v[206:209], v[90:93]
	v_mfma_f32_16x16x32_bf16 v[78:81], v[150:153], v[214:217], v[78:81]
	v_mfma_f32_16x16x32_bf16 v[74:77], v[158:161], v[214:217], v[74:77]
	v_mfma_f32_16x16x32_bf16 v[126:129], v[154:157], v[186:189], v[126:129]
	v_mfma_f32_16x16x32_bf16 v[122:125], v[162:165], v[186:189], v[122:125]
	v_mfma_f32_16x16x32_bf16 v[110:113], v[154:157], v[202:205], v[110:113]
	v_mfma_f32_16x16x32_bf16 v[106:109], v[162:165], v[202:205], v[106:109]
	v_mfma_f32_16x16x32_bf16 v[94:97], v[154:157], v[210:213], v[94:97]
	v_mfma_f32_16x16x32_bf16 v[90:93], v[162:165], v[210:213], v[90:93]
	v_mfma_f32_16x16x32_bf16 v[78:81], v[154:157], v[218:221], v[78:81]
	v_mfma_f32_16x16x32_bf16 v[74:77], v[162:165], v[218:221], v[74:77]
	v_mfma_f32_16x16x32_bf16 v[118:121], v[166:169], v[182:185], v[118:121]
	v_mfma_f32_16x16x32_bf16 v[114:117], v[174:177], v[182:185], v[114:117]
	v_mfma_f32_16x16x32_bf16 v[102:105], v[166:169], v[190:193], v[102:105]
	v_mfma_f32_16x16x32_bf16 v[98:101], v[174:177], v[190:193], v[98:101]
	v_mfma_f32_16x16x32_bf16 v[86:89], v[166:169], v[206:209], v[86:89]
	v_mfma_f32_16x16x32_bf16 v[82:85], v[174:177], v[206:209], v[82:85]
	v_mfma_f32_16x16x32_bf16 v[70:73], v[166:169], v[214:217], v[70:73]
	v_mfma_f32_16x16x32_bf16 v[66:69], v[174:177], v[214:217], v[66:69]
	v_mfma_f32_16x16x32_bf16 v[118:121], v[170:173], v[186:189], v[118:121]
	v_mfma_f32_16x16x32_bf16 v[114:117], v[178:181], v[186:189], v[114:117]
	v_mfma_f32_16x16x32_bf16 v[102:105], v[170:173], v[202:205], v[102:105]
	v_mfma_f32_16x16x32_bf16 v[98:101], v[178:181], v[202:205], v[98:101]
	v_mfma_f32_16x16x32_bf16 v[86:89], v[170:173], v[210:213], v[86:89]
	v_mfma_f32_16x16x32_bf16 v[82:85], v[178:181], v[210:213], v[82:85]
	v_mfma_f32_16x16x32_bf16 v[70:73], v[170:173], v[218:221], v[70:73]
	v_mfma_f32_16x16x32_bf16 v[66:69], v[178:181], v[218:221], v[66:69]
	s_barrier
	s_setprio 0
	s_add_i32 s54, s66, s58
	v_lshl_add_u64 v[142:143], v[142:143], 0, s[10:11]
	s_mov_b32 m0, s54
	ds_read_b128 v[182:185], v149 offset:49152
	ds_read_b128 v[186:189], v149 offset:50176
	ds_read_b128 v[190:193], v149 offset:51200
	ds_read_b128 v[202:205], v149 offset:52224
	ds_read_b128 v[206:209], v149 offset:53248
	ds_read_b128 v[210:213], v149 offset:54272
	ds_read_b128 v[214:217], v149 offset:55296
	ds_read_b128 v[218:221], v149 offset:56320
	s_add_i32 s49, s49, 2
	s_add_u32 s37, s37, 0x100
	s_addc_u32 s47, s47, 0
	s_add_u32 s12, s12, 0x100
	s_addc_u32 s13, s13, 0
	global_load_lds_dwordx4 v[142:143], off
	s_add_i32 m0, s54, 0x2000
	s_add_u32 s14, s14, 0x40080
	v_lshl_add_u64 v[142:143], v[222:223], 0, s[10:11]
	s_addc_u32 s15, s15, 0
	s_add_i32 s54, s67, s58
	global_load_lds_dwordx4 v[142:143], off
	v_lshl_add_u64 v[142:143], s[14:15], 0, v[0:1]
	s_mov_b32 m0, s54
	s_nop 0
	global_load_lds_dwordx4 v[142:143], off
	v_lshl_add_u64 v[142:143], s[14:15], 0, v[130:131]
	s_add_i32 m0, s54, 0x2000
	s_nop 0
	global_load_lds_dwordx4 v[142:143], off
	v_lshl_add_u64 v[142:143], v[232:233], 0, s[10:11]
	s_mov_b32 m0, s63
	s_nop 0
	global_load_lds_dwordx4 v[142:143], off
	v_lshl_add_u64 v[142:143], v[234:235], 0, s[10:11]
	s_mov_b32 m0, s64
	s_nop 0
	global_load_lds_dwordx4 v[142:143], off
	s_waitcnt vmcnt(8)
	s_waitcnt lgkmcnt(0)
	s_setprio 1
	s_barrier
	v_mfma_f32_16x16x32_bf16 v[62:65], v[150:153], v[182:185], v[62:65]
	v_mfma_f32_16x16x32_bf16 v[58:61], v[158:161], v[182:185], v[58:61]
	v_mfma_f32_16x16x32_bf16 v[46:49], v[150:153], v[190:193], v[46:49]
	v_mfma_f32_16x16x32_bf16 v[42:45], v[158:161], v[190:193], v[42:45]
	v_mfma_f32_16x16x32_bf16 v[30:33], v[150:153], v[206:209], v[30:33]
	v_mfma_f32_16x16x32_bf16 v[26:29], v[158:161], v[206:209], v[26:29]
	v_mfma_f32_16x16x32_bf16 v[14:17], v[150:153], v[214:217], v[14:17]
	v_mfma_f32_16x16x32_bf16 v[10:13], v[158:161], v[214:217], v[10:13]
	v_mfma_f32_16x16x32_bf16 v[62:65], v[154:157], v[186:189], v[62:65]
	v_mfma_f32_16x16x32_bf16 v[58:61], v[162:165], v[186:189], v[58:61]
	v_mfma_f32_16x16x32_bf16 v[46:49], v[154:157], v[202:205], v[46:49]
	v_mfma_f32_16x16x32_bf16 v[42:45], v[162:165], v[202:205], v[42:45]
	v_mfma_f32_16x16x32_bf16 v[30:33], v[154:157], v[210:213], v[30:33]
	v_mfma_f32_16x16x32_bf16 v[26:29], v[162:165], v[210:213], v[26:29]
	v_mfma_f32_16x16x32_bf16 v[14:17], v[154:157], v[218:221], v[14:17]
	v_mfma_f32_16x16x32_bf16 v[10:13], v[162:165], v[218:221], v[10:13]
	v_mfma_f32_16x16x32_bf16 v[54:57], v[166:169], v[182:185], v[54:57]
	v_mfma_f32_16x16x32_bf16 v[50:53], v[174:177], v[182:185], v[50:53]
	v_mfma_f32_16x16x32_bf16 v[38:41], v[166:169], v[190:193], v[38:41]
	v_mfma_f32_16x16x32_bf16 v[34:37], v[174:177], v[190:193], v[34:37]
	v_mfma_f32_16x16x32_bf16 v[22:25], v[166:169], v[206:209], v[22:25]
	v_mfma_f32_16x16x32_bf16 v[18:21], v[174:177], v[206:209], v[18:21]
	v_mfma_f32_16x16x32_bf16 v[6:9], v[166:169], v[214:217], v[6:9]
	v_mfma_f32_16x16x32_bf16 v[2:5], v[174:177], v[214:217], v[2:5]
	v_mfma_f32_16x16x32_bf16 v[54:57], v[170:173], v[186:189], v[54:57]
	v_mfma_f32_16x16x32_bf16 v[50:53], v[178:181], v[186:189], v[50:53]
	v_mfma_f32_16x16x32_bf16 v[38:41], v[170:173], v[202:205], v[38:41]
	v_mfma_f32_16x16x32_bf16 v[34:37], v[178:181], v[202:205], v[34:37]
	v_mfma_f32_16x16x32_bf16 v[22:25], v[170:173], v[210:213], v[22:25]
	v_mfma_f32_16x16x32_bf16 v[18:21], v[178:181], v[210:213], v[18:21]
	v_mfma_f32_16x16x32_bf16 v[6:9], v[170:173], v[218:221], v[6:9]
	v_mfma_f32_16x16x32_bf16 v[2:5], v[178:181], v[218:221], v[2:5]
	s_barrier
	s_setprio 0
	s_cmp_gt_u32 s49, 13
	s_cbranch_scc0 .LBB0_561
	s_and_b64 vcc, exec, s[44:45]
	s_cbranch_vccz .LBB0_564
	s_barrier

.LBB0_626:
	s_add_i32 s70, 0, 0x10000
	s_add_i32 s72, 0, 0x14000
	v_add_u32_e32 v134, s70, v183
	v_add_u32_e32 v168, s72, v183
	ds_read_b128 v[114:117], v134
	ds_read_b128 v[118:121], v134 offset:1024
	ds_read_b128 v[122:125], v134 offset:2048
	ds_read_b128 v[134:137], v134 offset:3072
	ds_read_b128 v[146:149], v168
	ds_read_b128 v[150:153], v168 offset:1024
	ds_read_b128 v[164:167], v168 offset:2048
	ds_read_b128 v[168:171], v168 offset:3072
	v_lshl_add_u64 v[180:181], s[12:13], 0, v[162:163]
	s_add_i32 m0, s63, 0xc000
	ds_read_b128 v[172:175], v185
	ds_read_b128 v[176:179], v185 offset:1024
	ds_read_b128 v[186:189], v185 offset:2048
	ds_read_b128 v[190:193], v185 offset:3072
	ds_read_b128 v[202:205], v185 offset:4096
	ds_read_b128 v[206:209], v185 offset:5120
	ds_read_b128 v[210:213], v185 offset:6144
	ds_read_b128 v[214:217], v185 offset:7168
	s_add_u32 s14, s12, 0xfff00080
	s_addc_u32 s15, s13, -1
	s_cmp_eq_u32 s53, 60
	s_cselect_b32 s59, s28, s15
	s_cselect_b32 s58, s29, s14
	s_cselect_b32 s15, s33, s51
	s_cselect_b32 s14, s36, s37
	global_load_lds_dwordx4 v[180:181], off
	v_lshl_add_u64 v[180:181], s[12:13], 0, v[160:161]
	s_add_i32 m0, s63, 0xe000
	s_nop 0
	global_load_lds_dwordx4 v[180:181], off
	s_waitcnt vmcnt(8)
	s_waitcnt lgkmcnt(0)
	s_setprio 1
	s_barrier
	v_mfma_f32_16x16x32_bf16 v[142:145], v[114:117], v[172:175], v[142:145]
	v_mfma_f32_16x16x32_bf16 v[138:141], v[122:125], v[172:175], v[138:141]
	v_mfma_f32_16x16x32_bf16 v[110:113], v[114:117], v[186:189], v[110:113]
	v_mfma_f32_16x16x32_bf16 v[106:109], v[122:125], v[186:189], v[106:109]
	v_mfma_f32_16x16x32_bf16 v[94:97], v[114:117], v[202:205], v[94:97]
	v_mfma_f32_16x16x32_bf16 v[90:93], v[122:125], v[202:205], v[90:93]
	v_mfma_f32_16x16x32_bf16 v[78:81], v[114:117], v[210:213], v[78:81]
	v_mfma_f32_16x16x32_bf16 v[74:77], v[122:125], v[210:213], v[74:77]
	v_mfma_f32_16x16x32_bf16 v[142:145], v[118:121], v[176:179], v[142:145]
	v_mfma_f32_16x16x32_bf16 v[138:141], v[134:137], v[176:179], v[138:141]
	v_mfma_f32_16x16x32_bf16 v[110:113], v[118:121], v[190:193], v[110:113]
	v_mfma_f32_16x16x32_bf16 v[106:109], v[134:137], v[190:193], v[106:109]
	v_mfma_f32_16x16x32_bf16 v[94:97], v[118:121], v[206:209], v[94:97]
	v_mfma_f32_16x16x32_bf16 v[90:93], v[134:137], v[206:209], v[90:93]
	v_mfma_f32_16x16x32_bf16 v[78:81], v[118:121], v[214:217], v[78:81]
	v_mfma_f32_16x16x32_bf16 v[74:77], v[134:137], v[214:217], v[74:77]
	v_mfma_f32_16x16x32_bf16 v[130:133], v[146:149], v[172:175], v[130:133]
	v_mfma_f32_16x16x32_bf16 v[126:129], v[164:167], v[172:175], v[126:129]
	v_mfma_f32_16x16x32_bf16 v[102:105], v[146:149], v[186:189], v[102:105]
	v_mfma_f32_16x16x32_bf16 v[98:101], v[164:167], v[186:189], v[98:101]
	v_mfma_f32_16x16x32_bf16 v[86:89], v[146:149], v[202:205], v[86:89]
	v_mfma_f32_16x16x32_bf16 v[82:85], v[164:167], v[202:205], v[82:85]
	v_mfma_f32_16x16x32_bf16 v[70:73], v[146:149], v[210:213], v[70:73]
	v_mfma_f32_16x16x32_bf16 v[66:69], v[164:167], v[210:213], v[66:69]
	v_mfma_f32_16x16x32_bf16 v[130:133], v[150:153], v[176:179], v[130:133]
	v_mfma_f32_16x16x32_bf16 v[126:129], v[168:171], v[176:179], v[126:129]
	v_mfma_f32_16x16x32_bf16 v[102:105], v[150:153], v[190:193], v[102:105]
	v_mfma_f32_16x16x32_bf16 v[98:101], v[168:171], v[190:193], v[98:101]
	v_mfma_f32_16x16x32_bf16 v[86:89], v[150:153], v[206:209], v[86:89]
	v_mfma_f32_16x16x32_bf16 v[82:85], v[168:171], v[206:209], v[82:85]
	v_mfma_f32_16x16x32_bf16 v[70:73], v[150:153], v[214:217], v[70:73]
	v_mfma_f32_16x16x32_bf16 v[66:69], v[168:171], v[214:217], v[66:69]
	s_barrier
	s_setprio 0
	s_add_i32 s70, s70, s62
	v_lshl_add_u64 v[180:181], s[14:15], 0, v[0:1]
	s_mov_b32 m0, s70
	ds_read_b128 v[172:175], v185 offset:16384
	ds_read_b128 v[176:179], v185 offset:17408
	ds_read_b128 v[186:189], v185 offset:18432
	ds_read_b128 v[190:193], v185 offset:19456
	ds_read_b128 v[202:205], v185 offset:20480
	ds_read_b128 v[206:209], v185 offset:21504
	ds_read_b128 v[210:213], v185 offset:22528
	ds_read_b128 v[214:217], v185 offset:23552
	global_load_lds_dwordx4 v[180:181], off
	s_add_i32 m0, s70, 0x2000
	s_add_u32 s70, s14, 0x100000
	v_lshl_add_u64 v[218:219], s[14:15], 0, v[154:155]
	s_addc_u32 s71, s15, 0
	s_add_i32 s72, s72, s62
	global_load_lds_dwordx4 v[218:219], off
	v_lshl_add_u64 v[220:221], s[70:71], 0, v[0:1]
	s_mov_b32 m0, s72
	v_lshl_add_u64 v[222:223], s[58:59], 0, v[156:157]
	global_load_lds_dwordx4 v[220:221], off
	v_lshl_add_u64 v[220:221], s[70:71], 0, v[154:155]
	s_add_i32 m0, s72, 0x2000
	s_nop 0
	global_load_lds_dwordx4 v[220:221], off
	v_lshl_add_u64 v[220:221], s[58:59], 0, v[158:159]
	s_mov_b32 m0, s63
	s_nop 0
	global_load_lds_dwordx4 v[220:221], off
	s_mov_b32 m0, s64
	s_nop 0
	global_load_lds_dwordx4 v[222:223], off
	s_waitcnt vmcnt(8)
	s_waitcnt lgkmcnt(0)
	s_setprio 1
	s_barrier
	v_mfma_f32_16x16x32_bf16 v[62:65], v[114:117], v[172:175], v[62:65]
	v_mfma_f32_16x16x32_bf16 v[58:61], v[122:125], v[172:175], v[58:61]
	v_mfma_f32_16x16x32_bf16 v[46:49], v[114:117], v[186:189], v[46:49]
	v_mfma_f32_16x16x32_bf16 v[42:45], v[122:125], v[186:189], v[42:45]
	v_mfma_f32_16x16x32_bf16 v[30:33], v[114:117], v[202:205], v[30:33]
	v_mfma_f32_16x16x32_bf16 v[26:29], v[122:125], v[202:205], v[26:29]
	v_mfma_f32_16x16x32_bf16 v[14:17], v[114:117], v[210:213], v[14:17]
	v_mfma_f32_16x16x32_bf16 v[10:13], v[122:125], v[210:213], v[10:13]
	v_mfma_f32_16x16x32_bf16 v[62:65], v[118:121], v[176:179], v[62:65]
	v_mfma_f32_16x16x32_bf16 v[58:61], v[134:137], v[176:179], v[58:61]
	v_mfma_f32_16x16x32_bf16 v[46:49], v[118:121], v[190:193], v[46:49]
	v_mfma_f32_16x16x32_bf16 v[42:45], v[134:137], v[190:193], v[42:45]
	v_mfma_f32_16x16x32_bf16 v[30:33], v[118:121], v[206:209], v[30:33]
	v_mfma_f32_16x16x32_bf16 v[26:29], v[134:137], v[206:209], v[26:29]
	v_mfma_f32_16x16x32_bf16 v[14:17], v[118:121], v[214:217], v[14:17]
	v_mfma_f32_16x16x32_bf16 v[10:13], v[134:137], v[214:217], v[10:13]
	v_mfma_f32_16x16x32_bf16 v[54:57], v[146:149], v[172:175], v[54:57]
	v_mfma_f32_16x16x32_bf16 v[50:53], v[164:167], v[172:175], v[50:53]
	v_mfma_f32_16x16x32_bf16 v[38:41], v[146:149], v[186:189], v[38:41]
	v_mfma_f32_16x16x32_bf16 v[34:37], v[164:167], v[186:189], v[34:37]
	v_mfma_f32_16x16x32_bf16 v[22:25], v[146:149], v[202:205], v[22:25]
	v_mfma_f32_16x16x32_bf16 v[18:21], v[164:167], v[202:205], v[18:21]
	v_mfma_f32_16x16x32_bf16 v[6:9], v[146:149], v[210:213], v[6:9]
	v_mfma_f32_16x16x32_bf16 v[2:5], v[164:167], v[210:213], v[2:5]
	v_mfma_f32_16x16x32_bf16 v[54:57], v[150:153], v[176:179], v[54:57]
	v_mfma_f32_16x16x32_bf16 v[50:53], v[168:171], v[176:179], v[50:53]
	v_mfma_f32_16x16x32_bf16 v[38:41], v[150:153], v[190:193], v[38:41]
	v_mfma_f32_16x16x32_bf16 v[34:37], v[168:171], v[190:193], v[34:37]
	v_mfma_f32_16x16x32_bf16 v[22:25], v[150:153], v[206:209], v[22:25]
	v_mfma_f32_16x16x32_bf16 v[18:21], v[168:171], v[206:209], v[18:21]
	v_mfma_f32_16x16x32_bf16 v[6:9], v[150:153], v[214:217], v[6:9]
	v_mfma_f32_16x16x32_bf16 v[2:5], v[168:171], v[214:217], v[2:5]
	s_barrier
	s_setprio 0
	s_add_i32 s70, 0, 0x18000
	s_add_i32 s71, 0, 0x1c000
	v_add_u32_e32 v134, s70, v183
	v_add_u32_e32 v168, s71, v183
	ds_read_b128 v[114:117], v134
	ds_read_b128 v[118:121], v134 offset:1024
	ds_read_b128 v[122:125], v134 offset:2048
	ds_read_b128 v[134:137], v134 offset:3072
	ds_read_b128 v[146:149], v168
	ds_read_b128 v[150:153], v168 offset:1024
	ds_read_b128 v[164:167], v168 offset:2048
	ds_read_b128 v[168:171], v168 offset:3072
	s_add_u32 s58, s58, 0x100000
	s_addc_u32 s59, s59, 0
	s_mov_b32 m0, s65
	v_lshl_add_u64 v[232:233], s[58:59], 0, v[158:159]
	ds_read_b128 v[172:175], v185 offset:32768
	ds_read_b128 v[176:179], v185 offset:33792
	ds_read_b128 v[186:189], v185 offset:34816
	ds_read_b128 v[190:193], v185 offset:35840
	ds_read_b128 v[202:205], v185 offset:36864
	ds_read_b128 v[206:209], v185 offset:37888
	ds_read_b128 v[210:213], v185 offset:38912
	ds_read_b128 v[214:217], v185 offset:39936
	global_load_lds_dwordx4 v[232:233], off
	v_lshl_add_u64 v[232:233], s[58:59], 0, v[156:157]
	s_mov_b32 m0, s66
	s_nop 0
	global_load_lds_dwordx4 v[232:233], off
	s_waitcnt vmcnt(8)
	s_waitcnt lgkmcnt(0)
	s_setprio 1
	s_barrier
	v_mfma_f32_16x16x32_bf16 v[142:145], v[114:117], v[172:175], v[142:145]
	v_mfma_f32_16x16x32_bf16 v[138:141], v[122:125], v[172:175], v[138:141]
	v_mfma_f32_16x16x32_bf16 v[110:113], v[114:117], v[186:189], v[110:113]
	v_mfma_f32_16x16x32_bf16 v[106:109], v[122:125], v[186:189], v[106:109]
	v_mfma_f32_16x16x32_bf16 v[94:97], v[114:117], v[202:205], v[94:97]
	v_mfma_f32_16x16x32_bf16 v[90:93], v[122:125], v[202:205], v[90:93]
	v_mfma_f32_16x16x32_bf16 v[78:81], v[114:117], v[210:213], v[78:81]
	v_mfma_f32_16x16x32_bf16 v[74:77], v[122:125], v[210:213], v[74:77]
	v_mfma_f32_16x16x32_bf16 v[142:145], v[118:121], v[176:179], v[142:145]
	v_mfma_f32_16x16x32_bf16 v[138:141], v[134:137], v[176:179], v[138:141]
	v_mfma_f32_16x16x32_bf16 v[110:113], v[118:121], v[190:193], v[110:113]
	v_mfma_f32_16x16x32_bf16 v[106:109], v[134:137], v[190:193], v[106:109]
	v_mfma_f32_16x16x32_bf16 v[94:97], v[118:121], v[206:209], v[94:97]
	v_mfma_f32_16x16x32_bf16 v[90:93], v[134:137], v[206:209], v[90:93]
	v_mfma_f32_16x16x32_bf16 v[78:81], v[118:121], v[214:217], v[78:81]
	v_mfma_f32_16x16x32_bf16 v[74:77], v[134:137], v[214:217], v[74:77]
	v_mfma_f32_16x16x32_bf16 v[130:133], v[146:149], v[172:175], v[130:133]
	v_mfma_f32_16x16x32_bf16 v[126:129], v[164:167], v[172:175], v[126:129]
	v_mfma_f32_16x16x32_bf16 v[102:105], v[146:149], v[186:189], v[102:105]
	v_mfma_f32_16x16x32_bf16 v[98:101], v[164:167], v[186:189], v[98:101]
	v_mfma_f32_16x16x32_bf16 v[86:89], v[146:149], v[202:205], v[86:89]
	v_mfma_f32_16x16x32_bf16 v[82:85], v[164:167], v[202:205], v[82:85]
	v_mfma_f32_16x16x32_bf16 v[70:73], v[146:149], v[210:213], v[70:73]
	v_mfma_f32_16x16x32_bf16 v[66:69], v[164:167], v[210:213], v[66:69]
	v_mfma_f32_16x16x32_bf16 v[130:133], v[150:153], v[176:179], v[130:133]
	v_mfma_f32_16x16x32_bf16 v[126:129], v[168:171], v[176:179], v[126:129]
	v_mfma_f32_16x16x32_bf16 v[102:105], v[150:153], v[190:193], v[102:105]
	v_mfma_f32_16x16x32_bf16 v[98:101], v[168:171], v[190:193], v[98:101]
	v_mfma_f32_16x16x32_bf16 v[86:89], v[150:153], v[206:209], v[86:89]
	v_mfma_f32_16x16x32_bf16 v[82:85], v[168:171], v[206:209], v[82:85]
	v_mfma_f32_16x16x32_bf16 v[70:73], v[150:153], v[214:217], v[70:73]
	v_mfma_f32_16x16x32_bf16 v[66:69], v[168:171], v[214:217], v[66:69]
	s_barrier
	s_setprio 0
	s_add_i32 s58, s70, s62
	v_lshl_add_u64 v[180:181], v[180:181], 0, s[10:11]
	s_mov_b32 m0, s58
	ds_read_b128 v[172:175], v185 offset:49152
	ds_read_b128 v[176:179], v185 offset:50176
	ds_read_b128 v[186:189], v185 offset:51200
	ds_read_b128 v[190:193], v185 offset:52224
	ds_read_b128 v[202:205], v185 offset:53248
	ds_read_b128 v[206:209], v185 offset:54272
	ds_read_b128 v[210:213], v185 offset:55296
	ds_read_b128 v[214:217], v185 offset:56320
	s_add_i32 s53, s53, 2
	s_add_u32 s37, s37, 0x100
	s_addc_u32 s51, s51, 0
	s_add_u32 s12, s12, 0x100
	s_addc_u32 s13, s13, 0
	global_load_lds_dwordx4 v[180:181], off
	s_add_i32 m0, s58, 0x2000
	s_add_u32 s14, s14, 0x100080
	v_lshl_add_u64 v[180:181], v[218:219], 0, s[10:11]
	s_addc_u32 s15, s15, 0
	s_add_i32 s58, s71, s62
	global_load_lds_dwordx4 v[180:181], off
	v_lshl_add_u64 v[180:181], s[14:15], 0, v[0:1]
	s_mov_b32 m0, s58
	s_nop 0
	global_load_lds_dwordx4 v[180:181], off
	v_lshl_add_u64 v[180:181], s[14:15], 0, v[154:155]
	s_add_i32 m0, s58, 0x2000
	s_nop 0
	global_load_lds_dwordx4 v[180:181], off
	v_lshl_add_u64 v[180:181], v[220:221], 0, s[10:11]
	s_mov_b32 m0, s67
	s_nop 0
	global_load_lds_dwordx4 v[180:181], off
	v_lshl_add_u64 v[180:181], v[222:223], 0, s[10:11]
	s_mov_b32 m0, s68
	s_nop 0
	global_load_lds_dwordx4 v[180:181], off
	s_waitcnt vmcnt(8)
	s_waitcnt lgkmcnt(0)
	s_setprio 1
	s_barrier
	v_mfma_f32_16x16x32_bf16 v[62:65], v[114:117], v[172:175], v[62:65]
	v_mfma_f32_16x16x32_bf16 v[58:61], v[122:125], v[172:175], v[58:61]
	v_mfma_f32_16x16x32_bf16 v[46:49], v[114:117], v[186:189], v[46:49]
	v_mfma_f32_16x16x32_bf16 v[42:45], v[122:125], v[186:189], v[42:45]
	v_mfma_f32_16x16x32_bf16 v[30:33], v[114:117], v[202:205], v[30:33]
	v_mfma_f32_16x16x32_bf16 v[26:29], v[122:125], v[202:205], v[26:29]
	v_mfma_f32_16x16x32_bf16 v[14:17], v[114:117], v[210:213], v[14:17]
	v_mfma_f32_16x16x32_bf16 v[10:13], v[122:125], v[210:213], v[10:13]
	v_mfma_f32_16x16x32_bf16 v[62:65], v[118:121], v[176:179], v[62:65]
	v_mfma_f32_16x16x32_bf16 v[58:61], v[134:137], v[176:179], v[58:61]
	v_mfma_f32_16x16x32_bf16 v[46:49], v[118:121], v[190:193], v[46:49]
	v_mfma_f32_16x16x32_bf16 v[42:45], v[134:137], v[190:193], v[42:45]
	v_mfma_f32_16x16x32_bf16 v[30:33], v[118:121], v[206:209], v[30:33]
	v_mfma_f32_16x16x32_bf16 v[26:29], v[134:137], v[206:209], v[26:29]
	v_mfma_f32_16x16x32_bf16 v[14:17], v[118:121], v[214:217], v[14:17]
	v_mfma_f32_16x16x32_bf16 v[10:13], v[134:137], v[214:217], v[10:13]
	v_mfma_f32_16x16x32_bf16 v[54:57], v[146:149], v[172:175], v[54:57]
	v_mfma_f32_16x16x32_bf16 v[50:53], v[164:167], v[172:175], v[50:53]
	v_mfma_f32_16x16x32_bf16 v[38:41], v[146:149], v[186:189], v[38:41]
	v_mfma_f32_16x16x32_bf16 v[34:37], v[164:167], v[186:189], v[34:37]
	v_mfma_f32_16x16x32_bf16 v[22:25], v[146:149], v[202:205], v[22:25]
	v_mfma_f32_16x16x32_bf16 v[18:21], v[164:167], v[202:205], v[18:21]
	v_mfma_f32_16x16x32_bf16 v[6:9], v[146:149], v[210:213], v[6:9]
	v_mfma_f32_16x16x32_bf16 v[2:5], v[164:167], v[210:213], v[2:5]
	v_mfma_f32_16x16x32_bf16 v[54:57], v[150:153], v[176:179], v[54:57]
	v_mfma_f32_16x16x32_bf16 v[50:53], v[168:171], v[176:179], v[50:53]
	v_mfma_f32_16x16x32_bf16 v[38:41], v[150:153], v[190:193], v[38:41]
	v_mfma_f32_16x16x32_bf16 v[34:37], v[168:171], v[190:193], v[34:37]
	v_mfma_f32_16x16x32_bf16 v[22:25], v[150:153], v[206:209], v[22:25]
	v_mfma_f32_16x16x32_bf16 v[18:21], v[168:171], v[206:209], v[18:21]
	v_mfma_f32_16x16x32_bf16 v[6:9], v[150:153], v[214:217], v[6:9]
	v_mfma_f32_16x16x32_bf16 v[2:5], v[168:171], v[214:217], v[2:5]
	s_barrier
	s_setprio 0
	s_cmp_gt_u32 s53, 61
	s_cbranch_scc0 .LBB0_626
	s_and_b64 vcc, exec, s[48:49]
	s_cbranch_vccz .LBB0_629
	s_barrier

.LBB0_731:
	s_add_u32 s37, s14, 0xfffc0080
	s_addc_u32 s51, s15, -1
	s_add_i32 s53, 0, 0x10000
	s_cmp_eq_u32 s36, 12
	s_cselect_b32 s63, s13, s51
	s_cselect_b32 s62, s20, s37
	s_cselect_b32 s61, s21, s33
	s_cselect_b32 s60, s28, s29
	s_add_i32 s37, 0, 0x14000
	v_add_u32_e32 v142, s53, v232
	v_add_u32_e32 v158, s37, v232
	ds_read_b128 v[126:129], v142
	ds_read_b128 v[134:137], v142 offset:1024
	ds_read_b128 v[138:141], v142 offset:2048
	ds_read_b128 v[142:145], v142 offset:3072
	ds_read_b128 v[146:149], v158
	ds_read_b128 v[150:153], v158 offset:1024
	ds_read_b128 v[154:157], v158 offset:2048
	ds_read_b128 v[158:161], v158 offset:3072
	v_lshl_add_u64 v[212:213], s[14:15], 0, v[210:211]
	s_add_i32 m0, s59, 0xc000
	ds_read_b128 v[162:165], v234
	ds_read_b128 v[166:169], v234 offset:1024
	ds_read_b128 v[170:173], v234 offset:2048
	ds_read_b128 v[174:177], v234 offset:3072
	ds_read_b128 v[178:181], v234 offset:4096
	ds_read_b128 v[182:185], v234 offset:5120
	ds_read_b128 v[186:189], v234 offset:6144
	ds_read_b128 v[190:193], v234 offset:7168
	global_load_lds_dwordx4 v[212:213], off
	v_lshl_add_u64 v[212:213], s[14:15], 0, v[208:209]
	s_add_i32 m0, s59, 0xe000
	s_nop 0
	global_load_lds_dwordx4 v[212:213], off
	s_waitcnt vmcnt(8)
	s_waitcnt lgkmcnt(0)
	s_setprio 1
	s_barrier
	v_mfma_f32_16x16x32_bf16 v[130:133], v[126:129], v[162:165], v[130:133]
	v_mfma_f32_16x16x32_bf16 v[122:125], v[138:141], v[162:165], v[122:125]
	v_mfma_f32_16x16x32_bf16 v[110:113], v[126:129], v[170:173], v[110:113]
	v_mfma_f32_16x16x32_bf16 v[106:109], v[138:141], v[170:173], v[106:109]
	v_mfma_f32_16x16x32_bf16 v[94:97], v[126:129], v[178:181], v[94:97]
	v_mfma_f32_16x16x32_bf16 v[90:93], v[138:141], v[178:181], v[90:93]
	v_mfma_f32_16x16x32_bf16 v[78:81], v[126:129], v[186:189], v[78:81]
	v_mfma_f32_16x16x32_bf16 v[74:77], v[138:141], v[186:189], v[74:77]
	v_mfma_f32_16x16x32_bf16 v[130:133], v[134:137], v[166:169], v[130:133]
	v_mfma_f32_16x16x32_bf16 v[122:125], v[142:145], v[166:169], v[122:125]
	v_mfma_f32_16x16x32_bf16 v[110:113], v[134:137], v[174:177], v[110:113]
	v_mfma_f32_16x16x32_bf16 v[106:109], v[142:145], v[174:177], v[106:109]
	v_mfma_f32_16x16x32_bf16 v[94:97], v[134:137], v[182:185], v[94:97]
	v_mfma_f32_16x16x32_bf16 v[90:93], v[142:145], v[182:185], v[90:93]
	v_mfma_f32_16x16x32_bf16 v[78:81], v[134:137], v[190:193], v[78:81]
	v_mfma_f32_16x16x32_bf16 v[74:77], v[142:145], v[190:193], v[74:77]
	v_mfma_f32_16x16x32_bf16 v[118:121], v[146:149], v[162:165], v[118:121]
	v_mfma_f32_16x16x32_bf16 v[114:117], v[154:157], v[162:165], v[114:117]
	v_mfma_f32_16x16x32_bf16 v[102:105], v[146:149], v[170:173], v[102:105]
	v_mfma_f32_16x16x32_bf16 v[98:101], v[154:157], v[170:173], v[98:101]
	v_mfma_f32_16x16x32_bf16 v[86:89], v[146:149], v[178:181], v[86:89]
	v_mfma_f32_16x16x32_bf16 v[82:85], v[154:157], v[178:181], v[82:85]
	v_mfma_f32_16x16x32_bf16 v[70:73], v[146:149], v[186:189], v[70:73]
	v_mfma_f32_16x16x32_bf16 v[66:69], v[154:157], v[186:189], v[66:69]
	v_mfma_f32_16x16x32_bf16 v[118:121], v[150:153], v[166:169], v[118:121]
	v_mfma_f32_16x16x32_bf16 v[114:117], v[158:161], v[166:169], v[114:117]
	v_mfma_f32_16x16x32_bf16 v[102:105], v[150:153], v[174:177], v[102:105]
	v_mfma_f32_16x16x32_bf16 v[98:101], v[158:161], v[174:177], v[98:101]
	v_mfma_f32_16x16x32_bf16 v[86:89], v[150:153], v[182:185], v[86:89]
	v_mfma_f32_16x16x32_bf16 v[82:85], v[158:161], v[182:185], v[82:85]
	v_mfma_f32_16x16x32_bf16 v[70:73], v[150:153], v[190:193], v[70:73]
	v_mfma_f32_16x16x32_bf16 v[66:69], v[158:161], v[190:193], v[66:69]
	s_barrier
	s_setprio 0
	s_add_i32 s51, s53, s66
	v_lshl_add_u64 v[212:213], s[60:61], 0, v[0:1]
	s_mov_b32 m0, s51
	ds_read_b128 v[162:165], v234 offset:16384
	ds_read_b128 v[166:169], v234 offset:17408
	ds_read_b128 v[170:173], v234 offset:18432
	ds_read_b128 v[174:177], v234 offset:19456
	ds_read_b128 v[178:181], v234 offset:20480
	ds_read_b128 v[182:185], v234 offset:21504
	ds_read_b128 v[186:189], v234 offset:22528
	ds_read_b128 v[190:193], v234 offset:23552
	global_load_lds_dwordx4 v[212:213], off
	s_add_i32 m0, s51, 0x2000
	s_add_u32 s74, s60, 0x40000
	v_lshl_add_u64 v[214:215], s[60:61], 0, v[202:203]
	s_addc_u32 s75, s61, 0
	s_add_i32 s37, s37, s66
	global_load_lds_dwordx4 v[214:215], off
	v_lshl_add_u64 v[216:217], s[74:75], 0, v[0:1]
	s_mov_b32 m0, s37
	v_lshl_add_u64 v[218:219], s[62:63], 0, v[204:205]
	global_load_lds_dwordx4 v[216:217], off
	v_lshl_add_u64 v[216:217], s[74:75], 0, v[202:203]
	s_add_i32 m0, s37, 0x2000
	s_nop 0
	global_load_lds_dwordx4 v[216:217], off
	v_lshl_add_u64 v[216:217], s[62:63], 0, v[206:207]
	s_mov_b32 m0, s59
	s_nop 0
	global_load_lds_dwordx4 v[216:217], off
	s_mov_b32 m0, s67
	s_nop 0
	global_load_lds_dwordx4 v[218:219], off
	s_waitcnt vmcnt(8)
	s_waitcnt lgkmcnt(0)
	s_setprio 1
	s_barrier
	v_mfma_f32_16x16x32_bf16 v[62:65], v[126:129], v[162:165], v[62:65]
	v_mfma_f32_16x16x32_bf16 v[58:61], v[138:141], v[162:165], v[58:61]
	v_mfma_f32_16x16x32_bf16 v[46:49], v[126:129], v[170:173], v[46:49]
	v_mfma_f32_16x16x32_bf16 v[42:45], v[138:141], v[170:173], v[42:45]
	v_mfma_f32_16x16x32_bf16 v[30:33], v[126:129], v[178:181], v[30:33]
	v_mfma_f32_16x16x32_bf16 v[26:29], v[138:141], v[178:181], v[26:29]
	v_mfma_f32_16x16x32_bf16 v[14:17], v[126:129], v[186:189], v[14:17]
	v_mfma_f32_16x16x32_bf16 v[10:13], v[138:141], v[186:189], v[10:13]
	v_mfma_f32_16x16x32_bf16 v[62:65], v[134:137], v[166:169], v[62:65]
	v_mfma_f32_16x16x32_bf16 v[58:61], v[142:145], v[166:169], v[58:61]
	v_mfma_f32_16x16x32_bf16 v[46:49], v[134:137], v[174:177], v[46:49]
	v_mfma_f32_16x16x32_bf16 v[42:45], v[142:145], v[174:177], v[42:45]
	v_mfma_f32_16x16x32_bf16 v[30:33], v[134:137], v[182:185], v[30:33]
	v_mfma_f32_16x16x32_bf16 v[26:29], v[142:145], v[182:185], v[26:29]
	v_mfma_f32_16x16x32_bf16 v[14:17], v[134:137], v[190:193], v[14:17]
	v_mfma_f32_16x16x32_bf16 v[10:13], v[142:145], v[190:193], v[10:13]
	v_mfma_f32_16x16x32_bf16 v[54:57], v[146:149], v[162:165], v[54:57]
	v_mfma_f32_16x16x32_bf16 v[50:53], v[154:157], v[162:165], v[50:53]
	v_mfma_f32_16x16x32_bf16 v[38:41], v[146:149], v[170:173], v[38:41]
	v_mfma_f32_16x16x32_bf16 v[34:37], v[154:157], v[170:173], v[34:37]
	v_mfma_f32_16x16x32_bf16 v[22:25], v[146:149], v[178:181], v[22:25]
	v_mfma_f32_16x16x32_bf16 v[18:21], v[154:157], v[178:181], v[18:21]
	v_mfma_f32_16x16x32_bf16 v[6:9], v[146:149], v[186:189], v[6:9]
	v_mfma_f32_16x16x32_bf16 v[2:5], v[154:157], v[186:189], v[2:5]
	v_mfma_f32_16x16x32_bf16 v[54:57], v[150:153], v[166:169], v[54:57]
	v_mfma_f32_16x16x32_bf16 v[50:53], v[158:161], v[166:169], v[50:53]
	v_mfma_f32_16x16x32_bf16 v[38:41], v[150:153], v[174:177], v[38:41]
	v_mfma_f32_16x16x32_bf16 v[34:37], v[158:161], v[174:177], v[34:37]
	v_mfma_f32_16x16x32_bf16 v[22:25], v[150:153], v[182:185], v[22:25]
	v_mfma_f32_16x16x32_bf16 v[18:21], v[158:161], v[182:185], v[18:21]
	v_mfma_f32_16x16x32_bf16 v[6:9], v[150:153], v[190:193], v[6:9]
	v_mfma_f32_16x16x32_bf16 v[2:5], v[158:161], v[190:193], v[2:5]
	s_barrier
	s_setprio 0
	s_add_i32 s37, 0, 0x18000
	s_add_i32 s51, 0, 0x1c000
	v_add_u32_e32 v142, s37, v232
	v_add_u32_e32 v158, s51, v232
	ds_read_b128 v[126:129], v142
	ds_read_b128 v[134:137], v142 offset:1024
	ds_read_b128 v[138:141], v142 offset:2048
	ds_read_b128 v[142:145], v142 offset:3072
	ds_read_b128 v[146:149], v158
	ds_read_b128 v[150:153], v158 offset:1024
	ds_read_b128 v[154:157], v158 offset:2048
	ds_read_b128 v[158:161], v158 offset:3072
	s_add_u32 s62, s62, 0x40000
	s_addc_u32 s63, s63, 0
	s_mov_b32 m0, s68
	v_lshl_add_u64 v[220:221], s[62:63], 0, v[206:207]
	ds_read_b128 v[162:165], v234 offset:32768
	ds_read_b128 v[166:169], v234 offset:33792
	ds_read_b128 v[170:173], v234 offset:34816
	ds_read_b128 v[174:177], v234 offset:35840
	ds_read_b128 v[178:181], v234 offset:36864
	ds_read_b128 v[182:185], v234 offset:37888
	ds_read_b128 v[186:189], v234 offset:38912
	ds_read_b128 v[190:193], v234 offset:39936
	global_load_lds_dwordx4 v[220:221], off
	v_lshl_add_u64 v[220:221], s[62:63], 0, v[204:205]
	s_mov_b32 m0, s69
	s_nop 0
	global_load_lds_dwordx4 v[220:221], off
	s_waitcnt vmcnt(8)
	s_waitcnt lgkmcnt(0)
	s_setprio 1
	s_barrier
	v_mfma_f32_16x16x32_bf16 v[130:133], v[126:129], v[162:165], v[130:133]
	v_mfma_f32_16x16x32_bf16 v[122:125], v[138:141], v[162:165], v[122:125]
	v_mfma_f32_16x16x32_bf16 v[110:113], v[126:129], v[170:173], v[110:113]
	v_mfma_f32_16x16x32_bf16 v[106:109], v[138:141], v[170:173], v[106:109]
	v_mfma_f32_16x16x32_bf16 v[94:97], v[126:129], v[178:181], v[94:97]
	v_mfma_f32_16x16x32_bf16 v[90:93], v[138:141], v[178:181], v[90:93]
	v_mfma_f32_16x16x32_bf16 v[78:81], v[126:129], v[186:189], v[78:81]
	v_mfma_f32_16x16x32_bf16 v[74:77], v[138:141], v[186:189], v[74:77]
	v_mfma_f32_16x16x32_bf16 v[130:133], v[134:137], v[166:169], v[130:133]
	v_mfma_f32_16x16x32_bf16 v[122:125], v[142:145], v[166:169], v[122:125]
	v_mfma_f32_16x16x32_bf16 v[110:113], v[134:137], v[174:177], v[110:113]
	v_mfma_f32_16x16x32_bf16 v[106:109], v[142:145], v[174:177], v[106:109]
	v_mfma_f32_16x16x32_bf16 v[94:97], v[134:137], v[182:185], v[94:97]
	v_mfma_f32_16x16x32_bf16 v[90:93], v[142:145], v[182:185], v[90:93]
	v_mfma_f32_16x16x32_bf16 v[78:81], v[134:137], v[190:193], v[78:81]
	v_mfma_f32_16x16x32_bf16 v[74:77], v[142:145], v[190:193], v[74:77]
	v_mfma_f32_16x16x32_bf16 v[118:121], v[146:149], v[162:165], v[118:121]
	v_mfma_f32_16x16x32_bf16 v[114:117], v[154:157], v[162:165], v[114:117]
	v_mfma_f32_16x16x32_bf16 v[102:105], v[146:149], v[170:173], v[102:105]
	v_mfma_f32_16x16x32_bf16 v[98:101], v[154:157], v[170:173], v[98:101]
	v_mfma_f32_16x16x32_bf16 v[86:89], v[146:149], v[178:181], v[86:89]
	v_mfma_f32_16x16x32_bf16 v[82:85], v[154:157], v[178:181], v[82:85]
	v_mfma_f32_16x16x32_bf16 v[70:73], v[146:149], v[186:189], v[70:73]
	v_mfma_f32_16x16x32_bf16 v[66:69], v[154:157], v[186:189], v[66:69]
	v_mfma_f32_16x16x32_bf16 v[118:121], v[150:153], v[166:169], v[118:121]
	v_mfma_f32_16x16x32_bf16 v[114:117], v[158:161], v[166:169], v[114:117]
	v_mfma_f32_16x16x32_bf16 v[102:105], v[150:153], v[174:177], v[102:105]
	v_mfma_f32_16x16x32_bf16 v[98:101], v[158:161], v[174:177], v[98:101]
	v_mfma_f32_16x16x32_bf16 v[86:89], v[150:153], v[182:185], v[86:89]
	v_mfma_f32_16x16x32_bf16 v[82:85], v[158:161], v[182:185], v[82:85]
	v_mfma_f32_16x16x32_bf16 v[70:73], v[150:153], v[190:193], v[70:73]
	v_mfma_f32_16x16x32_bf16 v[66:69], v[158:161], v[190:193], v[66:69]
	s_barrier
	s_setprio 0
	s_add_i32 s37, s37, s66
	v_lshl_add_u64 v[212:213], v[212:213], 0, s[10:11]
	s_mov_b32 m0, s37
	ds_read_b128 v[162:165], v234 offset:49152
	ds_read_b128 v[166:169], v234 offset:50176
	ds_read_b128 v[170:173], v234 offset:51200
	ds_read_b128 v[174:177], v234 offset:52224
	ds_read_b128 v[178:181], v234 offset:53248
	ds_read_b128 v[182:185], v234 offset:54272
	ds_read_b128 v[186:189], v234 offset:55296
	ds_read_b128 v[190:193], v234 offset:56320
	s_add_i32 s36, s36, 2
	s_add_u32 s29, s29, 0x100
	s_addc_u32 s33, s33, 0
	s_add_u32 s14, s14, 0x100
	s_addc_u32 s15, s15, 0
	global_load_lds_dwordx4 v[212:213], off
	s_add_i32 m0, s37, 0x2000
	s_add_u32 s60, s60, 0x40080
	v_lshl_add_u64 v[212:213], v[214:215], 0, s[10:11]
	s_addc_u32 s61, s61, 0
	s_add_i32 s37, s51, s66
	global_load_lds_dwordx4 v[212:213], off
	v_lshl_add_u64 v[212:213], s[60:61], 0, v[0:1]
	s_mov_b32 m0, s37
	s_nop 0
	global_load_lds_dwordx4 v[212:213], off
	v_lshl_add_u64 v[212:213], s[60:61], 0, v[202:203]
	s_add_i32 m0, s37, 0x2000
	s_nop 0
	global_load_lds_dwordx4 v[212:213], off
	v_lshl_add_u64 v[212:213], v[216:217], 0, s[10:11]
	s_mov_b32 m0, s70
	s_nop 0
	global_load_lds_dwordx4 v[212:213], off
	v_lshl_add_u64 v[212:213], v[218:219], 0, s[10:11]
	s_mov_b32 m0, s71
	s_nop 0
	global_load_lds_dwordx4 v[212:213], off
	s_waitcnt vmcnt(8)
	s_waitcnt lgkmcnt(0)
	s_setprio 1
	s_barrier
	v_mfma_f32_16x16x32_bf16 v[62:65], v[126:129], v[162:165], v[62:65]
	v_mfma_f32_16x16x32_bf16 v[58:61], v[138:141], v[162:165], v[58:61]
	v_mfma_f32_16x16x32_bf16 v[46:49], v[126:129], v[170:173], v[46:49]
	v_mfma_f32_16x16x32_bf16 v[42:45], v[138:141], v[170:173], v[42:45]
	v_mfma_f32_16x16x32_bf16 v[30:33], v[126:129], v[178:181], v[30:33]
	v_mfma_f32_16x16x32_bf16 v[26:29], v[138:141], v[178:181], v[26:29]
	v_mfma_f32_16x16x32_bf16 v[14:17], v[126:129], v[186:189], v[14:17]
	v_mfma_f32_16x16x32_bf16 v[10:13], v[138:141], v[186:189], v[10:13]
	v_mfma_f32_16x16x32_bf16 v[62:65], v[134:137], v[166:169], v[62:65]
	v_mfma_f32_16x16x32_bf16 v[58:61], v[142:145], v[166:169], v[58:61]
	v_mfma_f32_16x16x32_bf16 v[46:49], v[134:137], v[174:177], v[46:49]
	v_mfma_f32_16x16x32_bf16 v[42:45], v[142:145], v[174:177], v[42:45]
	v_mfma_f32_16x16x32_bf16 v[30:33], v[134:137], v[182:185], v[30:33]
	v_mfma_f32_16x16x32_bf16 v[26:29], v[142:145], v[182:185], v[26:29]
	v_mfma_f32_16x16x32_bf16 v[14:17], v[134:137], v[190:193], v[14:17]
	v_mfma_f32_16x16x32_bf16 v[10:13], v[142:145], v[190:193], v[10:13]
	v_mfma_f32_16x16x32_bf16 v[54:57], v[146:149], v[162:165], v[54:57]
	v_mfma_f32_16x16x32_bf16 v[50:53], v[154:157], v[162:165], v[50:53]
	v_mfma_f32_16x16x32_bf16 v[38:41], v[146:149], v[170:173], v[38:41]
	v_mfma_f32_16x16x32_bf16 v[34:37], v[154:157], v[170:173], v[34:37]
	v_mfma_f32_16x16x32_bf16 v[22:25], v[146:149], v[178:181], v[22:25]
	v_mfma_f32_16x16x32_bf16 v[18:21], v[154:157], v[178:181], v[18:21]
	v_mfma_f32_16x16x32_bf16 v[6:9], v[146:149], v[186:189], v[6:9]
	v_mfma_f32_16x16x32_bf16 v[2:5], v[154:157], v[186:189], v[2:5]
	v_mfma_f32_16x16x32_bf16 v[54:57], v[150:153], v[166:169], v[54:57]
	v_mfma_f32_16x16x32_bf16 v[50:53], v[158:161], v[166:169], v[50:53]
	v_mfma_f32_16x16x32_bf16 v[38:41], v[150:153], v[174:177], v[38:41]
	v_mfma_f32_16x16x32_bf16 v[34:37], v[158:161], v[174:177], v[34:37]
	v_mfma_f32_16x16x32_bf16 v[22:25], v[150:153], v[182:185], v[22:25]
	v_mfma_f32_16x16x32_bf16 v[18:21], v[158:161], v[182:185], v[18:21]
	v_mfma_f32_16x16x32_bf16 v[6:9], v[150:153], v[190:193], v[6:9]
	v_mfma_f32_16x16x32_bf16 v[2:5], v[158:161], v[190:193], v[2:5]
	s_barrier
	s_setprio 0
	s_cmp_gt_u32 s36, 13
	s_cbranch_scc0 .LBB0_731
	s_and_b64 vcc, exec, s[48:49]
	s_cbranch_vccz .LBB0_734
	s_barrier
